# hyena: all four FFT pass loops (fwd+inv, both orders) use A0+k*S leg addresses for strides >= 16
# baseline (speedup 1.0000x reference)
; DI float sin_t(float turns) { return __builtin_amdgcn_sinf(__builtin_amdgcn_fractf(turns)); }
; DI float cos_t(float turns) { return __builtin_amdgcn_cosf(__builtin_amdgcn_fractf(turns)); }
; DI float2 cmul(float2 a, float2 b) { return make_float2(a.x * b.x - a.y * b.y, a.x * b.y + a.y * b.x); }
; template <int N, bool INV>
; DI void fft_lds(float2* s) {
;     ...
;     for (int lq = 0; (1 << lq) <= top; lq += 2) {
;       const int q = 1 << lq;
;       __syncthreads();
;       const float inv4q = 1.0f / (float)(4 * q);
; #pragma unroll 4
;       for (int it = 0; it < N / 4 / NT; ++it) {
;         int idx = tid + it * NT;
;         int j = idx & (q - 1), blk = idx >> lq;
;         int p0 = blk * 4 * q + j;
;         float f = (float)j * inv4q;
;         float2 t1 = make_float2(cos_t(f), sin_t(f));
;         float2 t2 = cmul(t1, t1);
;         float2 x0 = s[phys(p0)], x1 = s[phys(p0 + q)], x2 = s[phys(p0 + 2 * q)], x3 = s[phys(p0 + 3 * q)];
;         float2 b = cmul(x1, t2);
;         float2 a0 = make_float2(x0.x + b.x, x0.y + b.y), a1 = make_float2(x0.x - b.x, x0.y - b.y);
;         b = cmul(x3, t2);
;         float2 a2 = make_float2(x2.x + b.x, x2.y + b.y), a3 = make_float2(x2.x - b.x, x2.y - b.y);
;         b = cmul(a2, t1);
;         s[phys(p0)] = make_float2(a0.x + b.x, a0.y + b.y);
;         s[phys(p0 + 2 * q)] = make_float2(a0.x - b.x, a0.y - b.y);
;         float2 c3 = cmul(a3, t1);
;         b = make_float2(-c3.y, c3.x);
;         s[phys(p0 + q)] = make_float2(a1.x + b.x, a1.y + b.y);
;         s[phys(p0 + 3 * q)] = make_float2(a1.x - b.x, a1.y - b.y);
;       }
.LBB0_484:
	s_lshl_b32 s11, s0, 23
	s_lshl_b32 s10, 4, s0
	s_sub_i32 s11, 0x3e800000, s11
	s_add_i32 s12, s1, -1
	s_mov_b32 s13, 0
	s_waitcnt lgkmcnt(0)
	s_barrier
	s_sub_i32 s32, s0, 4
	s_lshl_b32 s32, 0x88, s32
	s_cmp_lt_u32 s0, 4
	s_cbranch_scc0 .Lfft_fast_1
.LBB0_485:
	v_add_u32_e32 v20, s13, v1
	v_ashrrev_i32_e32 v2, s0, v20
	v_and_b32_e32 v7, s12, v20
	v_lshlrev_b32_e32 v8, 2, v2
	v_lshl_add_u32 v9, v8, s0, v7
	v_cvt_f32_u32_e32 v2, v7
	v_ashrrev_i32_e32 v10, 4, v9
	v_add_lshl_u32 v21, v10, v9, 3
	v_add_u32_e32 v9, s1, v9
	v_ashrrev_i32_e32 v10, 4, v9
	v_add_lshl_u32 v22, v10, v9, 3
	v_mul_f32_e32 v2, s11, v2
	v_or_b32_e32 v9, 2, v8
	v_or_b32_e32 v8, 3, v8
	v_fract_f32_e32 v3, v2
	v_lshl_add_u32 v9, v9, s0, v7
	v_lshl_add_u32 v7, v8, s0, v7
	v_cos_f32_e32 v2, v3
	v_sin_f32_e32 v3, v3
	v_ashrrev_i32_e32 v10, 4, v9
	v_ashrrev_i32_e32 v8, 4, v7
	v_add_lshl_u32 v23, v10, v9, 3
	v_lshlrev_b32_e32 v8, 3, v8
	v_lshlrev_b32_e32 v7, 3, v7
	v_add3_u32 v24, 0, v8, v7
	ds_read_b64 v[8:9], v21
	ds_read_b64 v[10:11], v22
	ds_read_b64 v[12:13], v23
	ds_read_b64 v[14:15], v24
	v_mul_f32_e32 v6, v2, v3
	v_pk_mul_f32 v[4:5], v[2:3], v[2:3]
	v_add_f32_e32 v6, v6, v6
	s_waitcnt lgkmcnt(2)
	v_pk_mul_f32 v[16:17], v[10:11], v[6:7] op_sel_hi:[1,0]
	v_pk_add_f32 v[4:5], v[4:5], v[4:5] op_sel:[0,1] op_sel_hi:[0,1] neg_lo:[0,1] neg_hi:[0,1]
	v_pk_fma_f32 v[18:19], v[10:11], v[4:5], v[16:17] op_sel:[0,0,1] op_sel_hi:[1,1,0] neg_lo:[0,0,1] neg_hi:[0,0,1]
	v_pk_fma_f32 v[10:11], v[10:11], v[4:5], v[16:17] op_sel:[0,0,1] op_sel_hi:[1,1,0]
	s_waitcnt lgkmcnt(0)
	v_pk_mul_f32 v[4:5], v[14:15], v[4:5]
	v_mov_b32_e32 v19, v11
	v_pk_fma_f32 v[16:17], v[14:15], v[6:7], v[4:5] op_sel:[0,0,1] op_sel_hi:[1,1,0]
	v_pk_fma_f32 v[4:5], v[14:15], v[6:7], v[4:5] op_sel:[0,0,1] op_sel_hi:[1,0,0] neg_lo:[1,0,0] neg_hi:[1,0,0]
	v_pk_add_f32 v[10:11], v[8:9], v[18:19] neg_lo:[0,1] neg_hi:[0,1]
	v_mov_b32_e32 v17, v5
	v_pk_add_f32 v[6:7], v[8:9], v[18:19]
	v_pk_add_f32 v[8:9], v[12:13], v[16:17] op_sel:[1,0] op_sel_hi:[0,1]
	v_pk_add_f32 v[4:5], v[12:13], v[16:17] op_sel:[1,0] op_sel_hi:[0,1] neg_lo:[0,1] neg_hi:[0,1]
	v_mov_b32_e32 v12, v3
	v_mov_b32_e32 v14, v3
	v_pk_mul_f32 v[16:17], v[2:3], v[8:9] op_sel_hi:[0,1]
	v_pk_fma_f32 v[12:13], v[12:13], v[8:9], v[16:17] op_sel:[0,0,1] op_sel_hi:[1,1,0] neg_lo:[1,0,0] neg_hi:[1,0,0]
	v_pk_fma_f32 v[8:9], v[14:15], v[8:9], v[16:17] op_sel:[0,0,1] op_sel_hi:[0,1,0]
	v_mov_b32_e32 v13, v9
	v_pk_add_f32 v[8:9], v[6:7], v[12:13]
	v_pk_add_f32 v[6:7], v[6:7], v[12:13] neg_lo:[0,1] neg_hi:[0,1]
	ds_write_b64 v21, v[8:9]
	ds_write_b64 v23, v[6:7]
	v_pk_mul_f32 v[6:7], v[14:15], v[4:5] op_sel_hi:[0,1]
	v_pk_fma_f32 v[8:9], v[2:3], v[4:5], v[6:7] op_sel:[0,0,1] op_sel_hi:[1,1,0]
	v_pk_fma_f32 v[2:3], v[2:3], v[4:5], v[6:7] op_sel:[0,0,1] op_sel_hi:[0,1,0] neg_lo:[0,0,1] neg_hi:[0,0,1]
	v_mov_b32_e32 v9, v3
	v_pk_add_f32 v[2:3], v[10:11], v[8:9] neg_lo:[0,1] neg_hi:[0,1]
	v_pk_add_f32 v[4:5], v[10:11], v[8:9]
	v_mov_b32_e32 v6, v2
	v_mov_b32_e32 v7, v5
	v_add_u32_e32 v2, 0x200, v20
	ds_write_b64 v22, v[6:7]
	v_and_b32_e32 v7, s12, v2
	v_ashrrev_i32_e32 v2, s0, v2
	v_lshlrev_b32_e32 v8, 2, v2
	v_lshl_add_u32 v9, v8, s0, v7
	v_cvt_f32_u32_e32 v2, v7
	v_ashrrev_i32_e32 v10, 4, v9
	v_add_lshl_u32 v21, v10, v9, 3
	v_add_u32_e32 v9, s1, v9
	v_ashrrev_i32_e32 v10, 4, v9
	v_add_lshl_u32 v22, v10, v9, 3
	v_mul_f32_e32 v2, s11, v2
	v_or_b32_e32 v9, 2, v8
	v_or_b32_e32 v8, 3, v8
	v_mov_b32_e32 v5, v3
	v_fract_f32_e32 v3, v2
	v_lshl_add_u32 v9, v9, s0, v7
	v_lshl_add_u32 v7, v8, s0, v7
	v_cos_f32_e32 v2, v3
	v_sin_f32_e32 v3, v3
	v_ashrrev_i32_e32 v10, 4, v9
	v_ashrrev_i32_e32 v8, 4, v7
	ds_write_b64 v24, v[4:5]
	v_add_lshl_u32 v23, v10, v9, 3
	v_lshlrev_b32_e32 v8, 3, v8
	v_lshlrev_b32_e32 v7, 3, v7
	v_add3_u32 v24, 0, v8, v7
	ds_read_b64 v[8:9], v21
	ds_read_b64 v[10:11], v22
	ds_read_b64 v[12:13], v23
	ds_read_b64 v[14:15], v24
	v_mul_f32_e32 v6, v2, v3
	v_pk_mul_f32 v[4:5], v[2:3], v[2:3]
	v_add_f32_e32 v6, v6, v6
	s_waitcnt lgkmcnt(2)
	v_pk_mul_f32 v[16:17], v[10:11], v[6:7] op_sel_hi:[1,0]
	v_pk_add_f32 v[4:5], v[4:5], v[4:5] op_sel:[0,1] op_sel_hi:[0,1] neg_lo:[0,1] neg_hi:[0,1]
	v_pk_fma_f32 v[18:19], v[10:11], v[4:5], v[16:17] op_sel:[0,0,1] op_sel_hi:[1,1,0] neg_lo:[0,0,1] neg_hi:[0,0,1]
	v_pk_fma_f32 v[10:11], v[10:11], v[4:5], v[16:17] op_sel:[0,0,1] op_sel_hi:[1,1,0]
	s_waitcnt lgkmcnt(0)
	v_pk_mul_f32 v[4:5], v[14:15], v[4:5]
	v_mov_b32_e32 v19, v11
	v_pk_fma_f32 v[16:17], v[14:15], v[6:7], v[4:5] op_sel:[0,0,1] op_sel_hi:[1,1,0]
	v_pk_fma_f32 v[4:5], v[14:15], v[6:7], v[4:5] op_sel:[0,0,1] op_sel_hi:[1,0,0] neg_lo:[1,0,0] neg_hi:[1,0,0]
	v_pk_add_f32 v[10:11], v[8:9], v[18:19] neg_lo:[0,1] neg_hi:[0,1]
	v_mov_b32_e32 v17, v5
	v_pk_add_f32 v[6:7], v[8:9], v[18:19]
	v_pk_add_f32 v[8:9], v[12:13], v[16:17] op_sel:[1,0] op_sel_hi:[0,1]
	v_pk_add_f32 v[4:5], v[12:13], v[16:17] op_sel:[1,0] op_sel_hi:[0,1] neg_lo:[0,1] neg_hi:[0,1]
	v_mov_b32_e32 v12, v3
	v_mov_b32_e32 v14, v3
	v_pk_mul_f32 v[16:17], v[2:3], v[8:9] op_sel_hi:[0,1]
	v_pk_fma_f32 v[12:13], v[12:13], v[8:9], v[16:17] op_sel:[0,0,1] op_sel_hi:[1,1,0] neg_lo:[1,0,0] neg_hi:[1,0,0]
	v_pk_fma_f32 v[8:9], v[14:15], v[8:9], v[16:17] op_sel:[0,0,1] op_sel_hi:[0,1,0]
	v_mov_b32_e32 v13, v9
	v_pk_add_f32 v[8:9], v[6:7], v[12:13]
	v_pk_add_f32 v[6:7], v[6:7], v[12:13] neg_lo:[0,1] neg_hi:[0,1]
	ds_write_b64 v21, v[8:9]
	ds_write_b64 v23, v[6:7]
	v_pk_mul_f32 v[6:7], v[14:15], v[4:5] op_sel_hi:[0,1]
	v_pk_fma_f32 v[8:9], v[2:3], v[4:5], v[6:7] op_sel:[0,0,1] op_sel_hi:[1,1,0]
	v_pk_fma_f32 v[2:3], v[2:3], v[4:5], v[6:7] op_sel:[0,0,1] op_sel_hi:[0,1,0] neg_lo:[0,0,1] neg_hi:[0,0,1]
	v_mov_b32_e32 v9, v3
	v_pk_add_f32 v[2:3], v[10:11], v[8:9] neg_lo:[0,1] neg_hi:[0,1]
	v_pk_add_f32 v[4:5], v[10:11], v[8:9]
	v_mov_b32_e32 v6, v2
	v_mov_b32_e32 v7, v5
	v_add_u32_e32 v2, 0x400, v20
	ds_write_b64 v22, v[6:7]
	v_and_b32_e32 v7, s12, v2
	v_ashrrev_i32_e32 v2, s0, v2
	v_lshlrev_b32_e32 v8, 2, v2
	v_lshl_add_u32 v9, v8, s0, v7
	v_cvt_f32_u32_e32 v2, v7
	v_ashrrev_i32_e32 v10, 4, v9
	v_add_lshl_u32 v21, v10, v9, 3
	v_add_u32_e32 v9, s1, v9
	v_ashrrev_i32_e32 v10, 4, v9
	v_add_lshl_u32 v22, v10, v9, 3
	v_mul_f32_e32 v2, s11, v2
	v_or_b32_e32 v9, 2, v8
	v_or_b32_e32 v8, 3, v8
	v_mov_b32_e32 v5, v3
	v_fract_f32_e32 v3, v2
	v_lshl_add_u32 v9, v9, s0, v7
	v_lshl_add_u32 v7, v8, s0, v7
	v_cos_f32_e32 v2, v3
	v_sin_f32_e32 v3, v3
	v_ashrrev_i32_e32 v10, 4, v9
	v_ashrrev_i32_e32 v8, 4, v7
	ds_write_b64 v24, v[4:5]
	v_add_lshl_u32 v23, v10, v9, 3
	v_lshlrev_b32_e32 v8, 3, v8
	v_lshlrev_b32_e32 v7, 3, v7
	v_add3_u32 v24, 0, v8, v7
	ds_read_b64 v[8:9], v21
	ds_read_b64 v[10:11], v22
	ds_read_b64 v[12:13], v23
	ds_read_b64 v[14:15], v24
	v_mul_f32_e32 v6, v2, v3
	v_pk_mul_f32 v[4:5], v[2:3], v[2:3]
	v_add_f32_e32 v6, v6, v6
	s_waitcnt lgkmcnt(2)
; DI float sin_t(float turns) { return __builtin_amdgcn_sinf(__builtin_amdgcn_fractf(turns)); }
; DI float cos_t(float turns) { return __builtin_amdgcn_cosf(__builtin_amdgcn_fractf(turns)); }
; DI float2 cmul(float2 a, float2 b) { return make_float2(a.x * b.x - a.y * b.y, a.x * b.y + a.y * b.x); }
; template <int N, bool INV>
; DI void fft_lds(float2* s) {
;     ...
; #pragma unroll 4
;       for (int it = 0; it < N / 4 / NT; ++it) {
;         int idx = tid + it * NT;
;         int j = idx & (q - 1), blk = idx >> lq;
;         int p0 = blk * 4 * q + j;
;         float f = (float)j * inv4q;
;         float2 t1 = make_float2(cos_t(f), sin_t(f));
;         float2 t2 = cmul(t1, t1);
;         float2 x0 = s[phys(p0)], x1 = s[phys(p0 + q)], x2 = s[phys(p0 + 2 * q)], x3 = s[phys(p0 + 3 * q)];
;         float2 b = cmul(x1, t2);
;         float2 a0 = make_float2(x0.x + b.x, x0.y + b.y), a1 = make_float2(x0.x - b.x, x0.y - b.y);
;         b = cmul(x3, t2);
;         float2 a2 = make_float2(x2.x + b.x, x2.y + b.y), a3 = make_float2(x2.x - b.x, x2.y - b.y);
;         b = cmul(a2, t1);
;         s[phys(p0)] = make_float2(a0.x + b.x, a0.y + b.y);
;         s[phys(p0 + 2 * q)] = make_float2(a0.x - b.x, a0.y - b.y);
;         float2 c3 = cmul(a3, t1);
;         b = make_float2(-c3.y, c3.x);
;         s[phys(p0 + q)] = make_float2(a1.x + b.x, a1.y + b.y);
;         s[phys(p0 + 3 * q)] = make_float2(a1.x - b.x, a1.y - b.y);
;       }
	v_pk_mul_f32 v[16:17], v[10:11], v[6:7] op_sel_hi:[1,0]
	v_pk_add_f32 v[4:5], v[4:5], v[4:5] op_sel:[0,1] op_sel_hi:[0,1] neg_lo:[0,1] neg_hi:[0,1]
	v_pk_fma_f32 v[18:19], v[10:11], v[4:5], v[16:17] op_sel:[0,0,1] op_sel_hi:[1,1,0] neg_lo:[0,0,1] neg_hi:[0,0,1]
	v_pk_fma_f32 v[10:11], v[10:11], v[4:5], v[16:17] op_sel:[0,0,1] op_sel_hi:[1,1,0]
	s_waitcnt lgkmcnt(0)
	v_pk_mul_f32 v[4:5], v[14:15], v[4:5]
	v_mov_b32_e32 v19, v11
	v_pk_fma_f32 v[16:17], v[14:15], v[6:7], v[4:5] op_sel:[0,0,1] op_sel_hi:[1,1,0]
	v_pk_fma_f32 v[4:5], v[14:15], v[6:7], v[4:5] op_sel:[0,0,1] op_sel_hi:[1,0,0] neg_lo:[1,0,0] neg_hi:[1,0,0]
	v_pk_add_f32 v[10:11], v[8:9], v[18:19] neg_lo:[0,1] neg_hi:[0,1]
	v_mov_b32_e32 v17, v5
	v_pk_add_f32 v[6:7], v[8:9], v[18:19]
	v_pk_add_f32 v[8:9], v[12:13], v[16:17] op_sel:[1,0] op_sel_hi:[0,1]
	v_pk_add_f32 v[4:5], v[12:13], v[16:17] op_sel:[1,0] op_sel_hi:[0,1] neg_lo:[0,1] neg_hi:[0,1]
	v_mov_b32_e32 v12, v3
	v_mov_b32_e32 v14, v3
	v_pk_mul_f32 v[16:17], v[2:3], v[8:9] op_sel_hi:[0,1]
	v_pk_fma_f32 v[12:13], v[12:13], v[8:9], v[16:17] op_sel:[0,0,1] op_sel_hi:[1,1,0] neg_lo:[1,0,0] neg_hi:[1,0,0]
	v_pk_fma_f32 v[8:9], v[14:15], v[8:9], v[16:17] op_sel:[0,0,1] op_sel_hi:[0,1,0]
	v_mov_b32_e32 v13, v9
	v_pk_add_f32 v[8:9], v[6:7], v[12:13]
	v_pk_add_f32 v[6:7], v[6:7], v[12:13] neg_lo:[0,1] neg_hi:[0,1]
	ds_write_b64 v21, v[8:9]
	ds_write_b64 v23, v[6:7]
	v_pk_mul_f32 v[6:7], v[14:15], v[4:5] op_sel_hi:[0,1]
	v_pk_fma_f32 v[8:9], v[2:3], v[4:5], v[6:7] op_sel:[0,0,1] op_sel_hi:[1,1,0]
	v_pk_fma_f32 v[2:3], v[2:3], v[4:5], v[6:7] op_sel:[0,0,1] op_sel_hi:[0,1,0] neg_lo:[0,0,1] neg_hi:[0,0,1]
	v_mov_b32_e32 v9, v3
	v_pk_add_f32 v[2:3], v[10:11], v[8:9] neg_lo:[0,1] neg_hi:[0,1]
	v_pk_add_f32 v[4:5], v[10:11], v[8:9]
	v_mov_b32_e32 v6, v2
	v_mov_b32_e32 v7, v5
	v_add_u32_e32 v2, 0x600, v20
	ds_write_b64 v22, v[6:7]
	v_and_b32_e32 v7, s12, v2
	v_ashrrev_i32_e32 v2, s0, v2
	v_lshlrev_b32_e32 v8, 2, v2
	v_lshl_add_u32 v9, v8, s0, v7
	v_cvt_f32_u32_e32 v2, v7
	v_ashrrev_i32_e32 v10, 4, v9
	v_add_lshl_u32 v20, v10, v9, 3
	v_add_u32_e32 v9, s1, v9
	v_ashrrev_i32_e32 v10, 4, v9
	v_add_lshl_u32 v21, v10, v9, 3
	v_mul_f32_e32 v2, s11, v2
	v_or_b32_e32 v9, 2, v8
	v_or_b32_e32 v8, 3, v8
	v_mov_b32_e32 v5, v3
	v_fract_f32_e32 v3, v2
	v_lshl_add_u32 v9, v9, s0, v7
	v_lshl_add_u32 v7, v8, s0, v7
	v_cos_f32_e32 v2, v3
	v_sin_f32_e32 v3, v3
	v_ashrrev_i32_e32 v10, 4, v9
	v_ashrrev_i32_e32 v8, 4, v7
	ds_write_b64 v24, v[4:5]
	v_add_lshl_u32 v22, v10, v9, 3
	v_lshlrev_b32_e32 v8, 3, v8
	v_lshlrev_b32_e32 v7, 3, v7
	v_add3_u32 v23, 0, v8, v7
	ds_read_b64 v[8:9], v20
	ds_read_b64 v[10:11], v21
	ds_read_b64 v[12:13], v22
	ds_read_b64 v[14:15], v23
	v_mul_f32_e32 v6, v2, v3
	v_pk_mul_f32 v[4:5], v[2:3], v[2:3]
	v_add_f32_e32 v6, v6, v6
	s_waitcnt lgkmcnt(2)
	v_pk_mul_f32 v[16:17], v[10:11], v[6:7] op_sel_hi:[1,0]
	v_pk_add_f32 v[4:5], v[4:5], v[4:5] op_sel:[0,1] op_sel_hi:[0,1] neg_lo:[0,1] neg_hi:[0,1]
	v_pk_fma_f32 v[18:19], v[10:11], v[4:5], v[16:17] op_sel:[0,0,1] op_sel_hi:[1,1,0] neg_lo:[0,0,1] neg_hi:[0,0,1]
	v_pk_fma_f32 v[10:11], v[10:11], v[4:5], v[16:17] op_sel:[0,0,1] op_sel_hi:[1,1,0]
	s_waitcnt lgkmcnt(0)
	v_pk_mul_f32 v[4:5], v[14:15], v[4:5]
	v_mov_b32_e32 v19, v11
	v_pk_fma_f32 v[16:17], v[14:15], v[6:7], v[4:5] op_sel:[0,0,1] op_sel_hi:[1,1,0]
	v_pk_fma_f32 v[4:5], v[14:15], v[6:7], v[4:5] op_sel:[0,0,1] op_sel_hi:[1,0,0] neg_lo:[1,0,0] neg_hi:[1,0,0]
	v_pk_add_f32 v[10:11], v[8:9], v[18:19] neg_lo:[0,1] neg_hi:[0,1]
	v_mov_b32_e32 v17, v5
	v_pk_add_f32 v[6:7], v[8:9], v[18:19]
	v_pk_add_f32 v[8:9], v[12:13], v[16:17] op_sel:[1,0] op_sel_hi:[0,1]
	v_pk_add_f32 v[4:5], v[12:13], v[16:17] op_sel:[1,0] op_sel_hi:[0,1] neg_lo:[0,1] neg_hi:[0,1]
	v_mov_b32_e32 v12, v3
	v_mov_b32_e32 v14, v3
	v_pk_mul_f32 v[16:17], v[2:3], v[8:9] op_sel_hi:[0,1]
	v_pk_fma_f32 v[12:13], v[12:13], v[8:9], v[16:17] op_sel:[0,0,1] op_sel_hi:[1,1,0] neg_lo:[1,0,0] neg_hi:[1,0,0]
	v_pk_fma_f32 v[8:9], v[14:15], v[8:9], v[16:17] op_sel:[0,0,1] op_sel_hi:[0,1,0]
	v_mov_b32_e32 v13, v9
	v_pk_add_f32 v[8:9], v[6:7], v[12:13]
	v_pk_add_f32 v[6:7], v[6:7], v[12:13] neg_lo:[0,1] neg_hi:[0,1]
	ds_write_b64 v20, v[8:9]
	ds_write_b64 v22, v[6:7]
	v_pk_mul_f32 v[6:7], v[14:15], v[4:5] op_sel_hi:[0,1]
	v_pk_fma_f32 v[8:9], v[2:3], v[4:5], v[6:7] op_sel:[0,0,1] op_sel_hi:[1,1,0]
	v_pk_fma_f32 v[2:3], v[2:3], v[4:5], v[6:7] op_sel:[0,0,1] op_sel_hi:[0,1,0] neg_lo:[0,0,1] neg_hi:[0,0,1]
	v_mov_b32_e32 v9, v3
	v_pk_add_f32 v[2:3], v[10:11], v[8:9] neg_lo:[0,1] neg_hi:[0,1]
	v_pk_add_f32 v[4:5], v[10:11], v[8:9]
	s_addk_i32 s13, 0x800
	v_mov_b32_e32 v6, v2
	v_mov_b32_e32 v7, v5
	v_mov_b32_e32 v5, v3
	s_cmpk_eq_i32 s13, 0x1000
	ds_write_b64 v21, v[6:7]
	ds_write_b64 v23, v[4:5]
	s_cbranch_scc0 .LBB0_485
	s_branch .Lfft_done_1
; DI float sin_t(float turns) { return __builtin_amdgcn_sinf(__builtin_amdgcn_fractf(turns)); }
; DI float cos_t(float turns) { return __builtin_amdgcn_cosf(__builtin_amdgcn_fractf(turns)); }
; DI float2 cmul(float2 a, float2 b) { return make_float2(a.x * b.x - a.y * b.y, a.x * b.y + a.y * b.x); }
; template <int N, bool INV>
; DI void fft_lds(float2* s) {
;     ...
; #pragma unroll 4
;       for (int it = 0; it < N / 4 / NT; ++it) {
;         int idx = tid + it * NT;
;         int j = idx & (q - 1), blk = idx >> lq;
;         int p0 = blk * 4 * q + j;
;         float f = (float)j * inv4q;
;         float2 t1 = make_float2(cos_t(f), sin_t(f));
;         float2 t2 = cmul(t1, t1);
;         float2 x0 = s[phys(p0)], x1 = s[phys(p0 + q)], x2 = s[phys(p0 + 2 * q)], x3 = s[phys(p0 + 3 * q)];
;         float2 b = cmul(x1, t2);
;         float2 a0 = make_float2(x0.x + b.x, x0.y + b.y), a1 = make_float2(x0.x - b.x, x0.y - b.y);
;         b = cmul(x3, t2);
;         float2 a2 = make_float2(x2.x + b.x, x2.y + b.y), a3 = make_float2(x2.x - b.x, x2.y - b.y);
;         b = cmul(a2, t1);
;         s[phys(p0)] = make_float2(a0.x + b.x, a0.y + b.y);
;         s[phys(p0 + 2 * q)] = make_float2(a0.x - b.x, a0.y - b.y);
;         float2 c3 = cmul(a3, t1);
;         b = make_float2(-c3.y, c3.x);
;         s[phys(p0 + q)] = make_float2(a1.x + b.x, a1.y + b.y);
;         s[phys(p0 + 3 * q)] = make_float2(a1.x - b.x, a1.y - b.y);
;       }
.Lfft_fast_1:
	v_add_u32_e32 v20, s13, v1
	v_ashrrev_i32_e32 v2, s0, v20
	v_and_b32_e32 v7, s12, v20
	v_lshlrev_b32_e32 v8, 2, v2
	v_lshl_add_u32 v9, v8, s0, v7
	v_cvt_f32_u32_e32 v2, v7
	v_ashrrev_i32_e32 v10, 4, v9
	v_add_lshl_u32 v21, v10, v9, 3
	v_mul_f32_e32 v2, s11, v2
	v_fract_f32_e32 v3, v2
	v_cos_f32_e32 v2, v3
	v_sin_f32_e32 v3, v3
	v_add_u32_e32 v22, s32, v21
	v_add_u32_e32 v23, s32, v22
	v_add_u32_e32 v24, s32, v23
	ds_read_b64 v[8:9], v21
	ds_read_b64 v[10:11], v22
	ds_read_b64 v[12:13], v23
	ds_read_b64 v[14:15], v24
	v_mul_f32_e32 v6, v2, v3
	v_pk_mul_f32 v[4:5], v[2:3], v[2:3]
	v_add_f32_e32 v6, v6, v6
	s_waitcnt lgkmcnt(2)
	v_pk_mul_f32 v[16:17], v[10:11], v[6:7] op_sel_hi:[1,0]
	v_pk_add_f32 v[4:5], v[4:5], v[4:5] op_sel:[0,1] op_sel_hi:[0,1] neg_lo:[0,1] neg_hi:[0,1]
	v_pk_fma_f32 v[18:19], v[10:11], v[4:5], v[16:17] op_sel:[0,0,1] op_sel_hi:[1,1,0] neg_lo:[0,0,1] neg_hi:[0,0,1]
	v_pk_fma_f32 v[10:11], v[10:11], v[4:5], v[16:17] op_sel:[0,0,1] op_sel_hi:[1,1,0]
	s_waitcnt lgkmcnt(0)
	v_pk_mul_f32 v[4:5], v[14:15], v[4:5]
	v_mov_b32_e32 v19, v11
	v_pk_fma_f32 v[16:17], v[14:15], v[6:7], v[4:5] op_sel:[0,0,1] op_sel_hi:[1,1,0]
	v_pk_fma_f32 v[4:5], v[14:15], v[6:7], v[4:5] op_sel:[0,0,1] op_sel_hi:[1,0,0] neg_lo:[1,0,0] neg_hi:[1,0,0]
	v_pk_add_f32 v[10:11], v[8:9], v[18:19] neg_lo:[0,1] neg_hi:[0,1]
	v_mov_b32_e32 v17, v5
	v_pk_add_f32 v[6:7], v[8:9], v[18:19]
	v_pk_add_f32 v[8:9], v[12:13], v[16:17] op_sel:[1,0] op_sel_hi:[0,1]
	v_pk_add_f32 v[4:5], v[12:13], v[16:17] op_sel:[1,0] op_sel_hi:[0,1] neg_lo:[0,1] neg_hi:[0,1]
	v_mov_b32_e32 v12, v3
	v_mov_b32_e32 v14, v3
	v_pk_mul_f32 v[16:17], v[2:3], v[8:9] op_sel_hi:[0,1]
	v_pk_fma_f32 v[12:13], v[12:13], v[8:9], v[16:17] op_sel:[0,0,1] op_sel_hi:[1,1,0] neg_lo:[1,0,0] neg_hi:[1,0,0]
	v_pk_fma_f32 v[8:9], v[14:15], v[8:9], v[16:17] op_sel:[0,0,1] op_sel_hi:[0,1,0]
	v_mov_b32_e32 v13, v9
	v_pk_add_f32 v[8:9], v[6:7], v[12:13]
	v_pk_add_f32 v[6:7], v[6:7], v[12:13] neg_lo:[0,1] neg_hi:[0,1]
	ds_write_b64 v21, v[8:9]
	ds_write_b64 v23, v[6:7]
	v_pk_mul_f32 v[6:7], v[14:15], v[4:5] op_sel_hi:[0,1]
	v_pk_fma_f32 v[8:9], v[2:3], v[4:5], v[6:7] op_sel:[0,0,1] op_sel_hi:[1,1,0]
	v_pk_fma_f32 v[2:3], v[2:3], v[4:5], v[6:7] op_sel:[0,0,1] op_sel_hi:[0,1,0] neg_lo:[0,0,1] neg_hi:[0,0,1]
	v_mov_b32_e32 v9, v3
	v_pk_add_f32 v[2:3], v[10:11], v[8:9] neg_lo:[0,1] neg_hi:[0,1]
	v_pk_add_f32 v[4:5], v[10:11], v[8:9]
	v_mov_b32_e32 v6, v2
	v_mov_b32_e32 v7, v5
	v_add_u32_e32 v2, 0x200, v20
	ds_write_b64 v22, v[6:7]
	v_and_b32_e32 v7, s12, v2
	v_ashrrev_i32_e32 v2, s0, v2
	v_lshlrev_b32_e32 v8, 2, v2
	v_lshl_add_u32 v9, v8, s0, v7
	v_cvt_f32_u32_e32 v2, v7
	v_ashrrev_i32_e32 v10, 4, v9
	v_add_lshl_u32 v21, v10, v9, 3
	v_mul_f32_e32 v2, s11, v2
	v_mov_b32_e32 v5, v3
	v_fract_f32_e32 v3, v2
	v_cos_f32_e32 v2, v3
	v_sin_f32_e32 v3, v3
	ds_write_b64 v24, v[4:5]
	v_add_u32_e32 v22, s32, v21
	v_add_u32_e32 v23, s32, v22
	v_add_u32_e32 v24, s32, v23
	ds_read_b64 v[8:9], v21
	ds_read_b64 v[10:11], v22
	ds_read_b64 v[12:13], v23
	ds_read_b64 v[14:15], v24
	v_mul_f32_e32 v6, v2, v3
	v_pk_mul_f32 v[4:5], v[2:3], v[2:3]
	v_add_f32_e32 v6, v6, v6
	s_waitcnt lgkmcnt(2)
	v_pk_mul_f32 v[16:17], v[10:11], v[6:7] op_sel_hi:[1,0]
	v_pk_add_f32 v[4:5], v[4:5], v[4:5] op_sel:[0,1] op_sel_hi:[0,1] neg_lo:[0,1] neg_hi:[0,1]
	v_pk_fma_f32 v[18:19], v[10:11], v[4:5], v[16:17] op_sel:[0,0,1] op_sel_hi:[1,1,0] neg_lo:[0,0,1] neg_hi:[0,0,1]
	v_pk_fma_f32 v[10:11], v[10:11], v[4:5], v[16:17] op_sel:[0,0,1] op_sel_hi:[1,1,0]
	s_waitcnt lgkmcnt(0)
	v_pk_mul_f32 v[4:5], v[14:15], v[4:5]
	v_mov_b32_e32 v19, v11
	v_pk_fma_f32 v[16:17], v[14:15], v[6:7], v[4:5] op_sel:[0,0,1] op_sel_hi:[1,1,0]
	v_pk_fma_f32 v[4:5], v[14:15], v[6:7], v[4:5] op_sel:[0,0,1] op_sel_hi:[1,0,0] neg_lo:[1,0,0] neg_hi:[1,0,0]
	v_pk_add_f32 v[10:11], v[8:9], v[18:19] neg_lo:[0,1] neg_hi:[0,1]
	v_mov_b32_e32 v17, v5
	v_pk_add_f32 v[6:7], v[8:9], v[18:19]
	v_pk_add_f32 v[8:9], v[12:13], v[16:17] op_sel:[1,0] op_sel_hi:[0,1]
	v_pk_add_f32 v[4:5], v[12:13], v[16:17] op_sel:[1,0] op_sel_hi:[0,1] neg_lo:[0,1] neg_hi:[0,1]
	v_mov_b32_e32 v12, v3
	v_mov_b32_e32 v14, v3
	v_pk_mul_f32 v[16:17], v[2:3], v[8:9] op_sel_hi:[0,1]
	v_pk_fma_f32 v[12:13], v[12:13], v[8:9], v[16:17] op_sel:[0,0,1] op_sel_hi:[1,1,0] neg_lo:[1,0,0] neg_hi:[1,0,0]
	v_pk_fma_f32 v[8:9], v[14:15], v[8:9], v[16:17] op_sel:[0,0,1] op_sel_hi:[0,1,0]
	v_mov_b32_e32 v13, v9
	v_pk_add_f32 v[8:9], v[6:7], v[12:13]
	v_pk_add_f32 v[6:7], v[6:7], v[12:13] neg_lo:[0,1] neg_hi:[0,1]
	ds_write_b64 v21, v[8:9]
	ds_write_b64 v23, v[6:7]
	v_pk_mul_f32 v[6:7], v[14:15], v[4:5] op_sel_hi:[0,1]
	v_pk_fma_f32 v[8:9], v[2:3], v[4:5], v[6:7] op_sel:[0,0,1] op_sel_hi:[1,1,0]
	v_pk_fma_f32 v[2:3], v[2:3], v[4:5], v[6:7] op_sel:[0,0,1] op_sel_hi:[0,1,0] neg_lo:[0,0,1] neg_hi:[0,0,1]
	v_mov_b32_e32 v9, v3
	v_pk_add_f32 v[2:3], v[10:11], v[8:9] neg_lo:[0,1] neg_hi:[0,1]
	v_pk_add_f32 v[4:5], v[10:11], v[8:9]
	v_mov_b32_e32 v6, v2
	v_mov_b32_e32 v7, v5
	v_add_u32_e32 v2, 0x400, v20
	ds_write_b64 v22, v[6:7]
	v_and_b32_e32 v7, s12, v2
	v_ashrrev_i32_e32 v2, s0, v2
	v_lshlrev_b32_e32 v8, 2, v2
	v_lshl_add_u32 v9, v8, s0, v7
	v_cvt_f32_u32_e32 v2, v7
	v_ashrrev_i32_e32 v10, 4, v9
	v_add_lshl_u32 v21, v10, v9, 3
	v_mul_f32_e32 v2, s11, v2
	v_mov_b32_e32 v5, v3
	v_fract_f32_e32 v3, v2
	v_cos_f32_e32 v2, v3
	v_sin_f32_e32 v3, v3
	ds_write_b64 v24, v[4:5]
	v_add_u32_e32 v22, s32, v21
	v_add_u32_e32 v23, s32, v22
	v_add_u32_e32 v24, s32, v23
	ds_read_b64 v[8:9], v21
	ds_read_b64 v[10:11], v22
	ds_read_b64 v[12:13], v23
	ds_read_b64 v[14:15], v24
	v_mul_f32_e32 v6, v2, v3
	v_pk_mul_f32 v[4:5], v[2:3], v[2:3]
	v_add_f32_e32 v6, v6, v6
	s_waitcnt lgkmcnt(2)
; DI float sin_t(float turns) { return __builtin_amdgcn_sinf(__builtin_amdgcn_fractf(turns)); }
; DI float cos_t(float turns) { return __builtin_amdgcn_cosf(__builtin_amdgcn_fractf(turns)); }
; DI float2 cmul(float2 a, float2 b) { return make_float2(a.x * b.x - a.y * b.y, a.x * b.y + a.y * b.x); }
; template <int N, bool INV>
; DI void fft_lds(float2* s) {
;     ...
; #pragma unroll 4
;       for (int it = 0; it < N / 4 / NT; ++it) {
;         int idx = tid + it * NT;
;         int j = idx & (q - 1), blk = idx >> lq;
;         int p0 = blk * 4 * q + j;
;         float f = (float)j * inv4q;
;         float2 t1 = make_float2(cos_t(f), sin_t(f));
;         float2 t2 = cmul(t1, t1);
;         float2 x0 = s[phys(p0)], x1 = s[phys(p0 + q)], x2 = s[phys(p0 + 2 * q)], x3 = s[phys(p0 + 3 * q)];
;         float2 b = cmul(x1, t2);
;         float2 a0 = make_float2(x0.x + b.x, x0.y + b.y), a1 = make_float2(x0.x - b.x, x0.y - b.y);
;         b = cmul(x3, t2);
;         float2 a2 = make_float2(x2.x + b.x, x2.y + b.y), a3 = make_float2(x2.x - b.x, x2.y - b.y);
;         b = cmul(a2, t1);
;         s[phys(p0)] = make_float2(a0.x + b.x, a0.y + b.y);
;         s[phys(p0 + 2 * q)] = make_float2(a0.x - b.x, a0.y - b.y);
;         float2 c3 = cmul(a3, t1);
;         b = make_float2(-c3.y, c3.x);
;         s[phys(p0 + q)] = make_float2(a1.x + b.x, a1.y + b.y);
;         s[phys(p0 + 3 * q)] = make_float2(a1.x - b.x, a1.y - b.y);
;       }
	v_pk_mul_f32 v[16:17], v[10:11], v[6:7] op_sel_hi:[1,0]
	v_pk_add_f32 v[4:5], v[4:5], v[4:5] op_sel:[0,1] op_sel_hi:[0,1] neg_lo:[0,1] neg_hi:[0,1]
	v_pk_fma_f32 v[18:19], v[10:11], v[4:5], v[16:17] op_sel:[0,0,1] op_sel_hi:[1,1,0] neg_lo:[0,0,1] neg_hi:[0,0,1]
	v_pk_fma_f32 v[10:11], v[10:11], v[4:5], v[16:17] op_sel:[0,0,1] op_sel_hi:[1,1,0]
	s_waitcnt lgkmcnt(0)
	v_pk_mul_f32 v[4:5], v[14:15], v[4:5]
	v_mov_b32_e32 v19, v11
	v_pk_fma_f32 v[16:17], v[14:15], v[6:7], v[4:5] op_sel:[0,0,1] op_sel_hi:[1,1,0]
	v_pk_fma_f32 v[4:5], v[14:15], v[6:7], v[4:5] op_sel:[0,0,1] op_sel_hi:[1,0,0] neg_lo:[1,0,0] neg_hi:[1,0,0]
	v_pk_add_f32 v[10:11], v[8:9], v[18:19] neg_lo:[0,1] neg_hi:[0,1]
	v_mov_b32_e32 v17, v5
	v_pk_add_f32 v[6:7], v[8:9], v[18:19]
	v_pk_add_f32 v[8:9], v[12:13], v[16:17] op_sel:[1,0] op_sel_hi:[0,1]
	v_pk_add_f32 v[4:5], v[12:13], v[16:17] op_sel:[1,0] op_sel_hi:[0,1] neg_lo:[0,1] neg_hi:[0,1]
	v_mov_b32_e32 v12, v3
	v_mov_b32_e32 v14, v3
	v_pk_mul_f32 v[16:17], v[2:3], v[8:9] op_sel_hi:[0,1]
	v_pk_fma_f32 v[12:13], v[12:13], v[8:9], v[16:17] op_sel:[0,0,1] op_sel_hi:[1,1,0] neg_lo:[1,0,0] neg_hi:[1,0,0]
	v_pk_fma_f32 v[8:9], v[14:15], v[8:9], v[16:17] op_sel:[0,0,1] op_sel_hi:[0,1,0]
	v_mov_b32_e32 v13, v9
	v_pk_add_f32 v[8:9], v[6:7], v[12:13]
	v_pk_add_f32 v[6:7], v[6:7], v[12:13] neg_lo:[0,1] neg_hi:[0,1]
	ds_write_b64 v21, v[8:9]
	ds_write_b64 v23, v[6:7]
	v_pk_mul_f32 v[6:7], v[14:15], v[4:5] op_sel_hi:[0,1]
	v_pk_fma_f32 v[8:9], v[2:3], v[4:5], v[6:7] op_sel:[0,0,1] op_sel_hi:[1,1,0]
	v_pk_fma_f32 v[2:3], v[2:3], v[4:5], v[6:7] op_sel:[0,0,1] op_sel_hi:[0,1,0] neg_lo:[0,0,1] neg_hi:[0,0,1]
	v_mov_b32_e32 v9, v3
	v_pk_add_f32 v[2:3], v[10:11], v[8:9] neg_lo:[0,1] neg_hi:[0,1]
	v_pk_add_f32 v[4:5], v[10:11], v[8:9]
	v_mov_b32_e32 v6, v2
	v_mov_b32_e32 v7, v5
	v_add_u32_e32 v2, 0x600, v20
	ds_write_b64 v22, v[6:7]
	v_and_b32_e32 v7, s12, v2
	v_ashrrev_i32_e32 v2, s0, v2
	v_lshlrev_b32_e32 v8, 2, v2
	v_lshl_add_u32 v9, v8, s0, v7
	v_cvt_f32_u32_e32 v2, v7
	v_ashrrev_i32_e32 v10, 4, v9
	v_add_lshl_u32 v20, v10, v9, 3
	v_mul_f32_e32 v2, s11, v2
	v_mov_b32_e32 v5, v3
	v_fract_f32_e32 v3, v2
	v_cos_f32_e32 v2, v3
	v_sin_f32_e32 v3, v3
	ds_write_b64 v24, v[4:5]
	v_add_u32_e32 v21, s32, v20
	v_add_u32_e32 v22, s32, v21
	v_add_u32_e32 v23, s32, v22
	ds_read_b64 v[8:9], v20
	ds_read_b64 v[10:11], v21
	ds_read_b64 v[12:13], v22
	ds_read_b64 v[14:15], v23
	v_mul_f32_e32 v6, v2, v3
	v_pk_mul_f32 v[4:5], v[2:3], v[2:3]
	v_add_f32_e32 v6, v6, v6
	s_waitcnt lgkmcnt(2)
	v_pk_mul_f32 v[16:17], v[10:11], v[6:7] op_sel_hi:[1,0]
	v_pk_add_f32 v[4:5], v[4:5], v[4:5] op_sel:[0,1] op_sel_hi:[0,1] neg_lo:[0,1] neg_hi:[0,1]
	v_pk_fma_f32 v[18:19], v[10:11], v[4:5], v[16:17] op_sel:[0,0,1] op_sel_hi:[1,1,0] neg_lo:[0,0,1] neg_hi:[0,0,1]
	v_pk_fma_f32 v[10:11], v[10:11], v[4:5], v[16:17] op_sel:[0,0,1] op_sel_hi:[1,1,0]
	s_waitcnt lgkmcnt(0)
	v_pk_mul_f32 v[4:5], v[14:15], v[4:5]
	v_mov_b32_e32 v19, v11
	v_pk_fma_f32 v[16:17], v[14:15], v[6:7], v[4:5] op_sel:[0,0,1] op_sel_hi:[1,1,0]
	v_pk_fma_f32 v[4:5], v[14:15], v[6:7], v[4:5] op_sel:[0,0,1] op_sel_hi:[1,0,0] neg_lo:[1,0,0] neg_hi:[1,0,0]
	v_pk_add_f32 v[10:11], v[8:9], v[18:19] neg_lo:[0,1] neg_hi:[0,1]
	v_mov_b32_e32 v17, v5
	v_pk_add_f32 v[6:7], v[8:9], v[18:19]
	v_pk_add_f32 v[8:9], v[12:13], v[16:17] op_sel:[1,0] op_sel_hi:[0,1]
	v_pk_add_f32 v[4:5], v[12:13], v[16:17] op_sel:[1,0] op_sel_hi:[0,1] neg_lo:[0,1] neg_hi:[0,1]
	v_mov_b32_e32 v12, v3
	v_mov_b32_e32 v14, v3
	v_pk_mul_f32 v[16:17], v[2:3], v[8:9] op_sel_hi:[0,1]
	v_pk_fma_f32 v[12:13], v[12:13], v[8:9], v[16:17] op_sel:[0,0,1] op_sel_hi:[1,1,0] neg_lo:[1,0,0] neg_hi:[1,0,0]
	v_pk_fma_f32 v[8:9], v[14:15], v[8:9], v[16:17] op_sel:[0,0,1] op_sel_hi:[0,1,0]
	v_mov_b32_e32 v13, v9
	v_pk_add_f32 v[8:9], v[6:7], v[12:13]
	v_pk_add_f32 v[6:7], v[6:7], v[12:13] neg_lo:[0,1] neg_hi:[0,1]
	ds_write_b64 v20, v[8:9]
	ds_write_b64 v22, v[6:7]
	v_pk_mul_f32 v[6:7], v[14:15], v[4:5] op_sel_hi:[0,1]
	v_pk_fma_f32 v[8:9], v[2:3], v[4:5], v[6:7] op_sel:[0,0,1] op_sel_hi:[1,1,0]
	v_pk_fma_f32 v[2:3], v[2:3], v[4:5], v[6:7] op_sel:[0,0,1] op_sel_hi:[0,1,0] neg_lo:[0,0,1] neg_hi:[0,0,1]
	v_mov_b32_e32 v9, v3
	v_pk_add_f32 v[2:3], v[10:11], v[8:9] neg_lo:[0,1] neg_hi:[0,1]
	v_pk_add_f32 v[4:5], v[10:11], v[8:9]
	s_addk_i32 s13, 0x800
	v_mov_b32_e32 v6, v2
	v_mov_b32_e32 v7, v5
	v_mov_b32_e32 v5, v3
	s_cmpk_eq_i32 s13, 0x1000
	ds_write_b64 v21, v[6:7]
	ds_write_b64 v23, v[4:5]
	s_cbranch_scc0 .Lfft_fast_1
; template <int N, bool INV>
; DI void fft_lds(float2* s) {
;     ...
;     for (int lq = 0; (1 << lq) <= top; lq += 2) {
;       const int q = 1 << lq;
;       __syncthreads();
; DI void hyena_lat_item(const P& p, int l, int c, int bp, unsigned char* lds) {
;     ...
;     const float bias = p.in[I_HBIAS][l * 512 + ord * 256 + c];
;     if (ord == 0) {
;       float2 y1v[16];
; #pragma unroll
;       for (int i = 0; i < 16; ++i) {
;         int n = (i >> 3) * 4096 + tid * 8 + (i & 7);
;         float2 cv = s[phys(n)], v = scr[n], x1 = scr[8192 + n];
;         y1v[i] = make_float2(x1.x * (cv.x * invN + v.x * bias), x1.y * (cv.y * invN + v.y * bias));
;         scr[24576 + n] = y1v[i];
.Lfft_done_1:
	s_add_i32 s11, s0, 2
	s_cmp_gt_u32 s0, 10
	s_mov_b32 s1, s10
	s_mov_b32 s0, s11
	s_cbranch_scc0 .LBB0_484
	v_readlane_b32 s0, v254, 55
	s_add_i32 s0, s6, s0
	s_ashr_i32 s1, s0, 31
	v_readlane_b32 s16, v252, 46
	s_lshl_b64 s[0:1], s[0:1], 2
	v_readlane_b32 s22, v252, 52
	v_lshlrev_b32_e32 v1, 2, v52
	v_ashrrev_i32_e32 v51, 31, v50
	v_readlane_b32 s23, v252, 53
	s_add_u32 s0, s22, s0
	v_and_b32_e32 v1, -8, v1
	v_lshlrev_b32_e32 v38, 3, v50
	s_addc_u32 s1, s23, s1
	v_add3_u32 v63, 0, v1, v38
	v_lshl_add_u64 v[58:59], v[50:51], 3, s[56:57]
	s_waitcnt lgkmcnt(0)
	s_barrier
	global_load_dword v62, v179, s[0:1]
	ds_read2_b64 v[2:5], v63 offset1:1
	global_load_dwordx4 v[18:21], v[58:59], off offset:48
	global_load_dwordx4 v[6:9], v[58:59], off offset:32
	global_load_dwordx4 v[10:13], v[58:59], off offset:16
	global_load_dwordx4 v[14:17], v[58:59], off
	s_mov_b64 s[12:13], 0x10000
	v_add_co_u32_e32 v22, vcc, s65, v58
	v_lshl_add_u64 v[34:35], v[58:59], 0, s[12:13]
	s_nop 0
	v_addc_co_u32_e32 v23, vcc, 0, v59, vcc
	global_load_dwordx4 v[22:25], v[22:23], off
	s_nop 0
	global_load_dwordx4 v[26:29], v[34:35], off offset:48
	global_load_dwordx4 v[30:33], v[34:35], off offset:32
	s_nop 0
	global_load_dwordx4 v[34:37], v[34:35], off offset:16
	v_readlane_b32 s18, v252, 48
	v_readlane_b32 s19, v252, 49
	s_mov_b32 s18, 0x38800000
	s_mov_b32 s10, 0x30000
	s_mov_b64 s[0:1], 0x38000
	v_lshl_add_u64 v[48:49], v[58:59], 0, s[0:1]
	s_mov_b32 s0, 0x18000
	v_add_u32_e32 v1, 0x1000, v50
	v_ashrrev_i32_e32 v1, 4, v1
	v_lshlrev_b32_e32 v1, 3, v1
	v_add3_u32 v53, 0, v1, v38
	v_add_u32_e32 v1, 0x8000, v53
	v_readlane_b32 s17, v252, 47
	s_mov_b64 s[16:17], 0x30000
	v_lshl_add_u64 v[46:47], v[58:59], 0, s[78:79]
	v_lshl_add_u64 v[60:61], v[58:59], 0, s[16:17]
	v_readlane_b32 s20, v252, 50
	v_readlane_b32 s21, v252, 51
	v_readlane_b32 s24, v252, 54
	v_readlane_b32 s25, v252, 55
	v_readlane_b32 s26, v252, 56
	v_readlane_b32 s27, v252, 57
	v_readlane_b32 s28, v252, 58
	v_readlane_b32 s29, v252, 59
	v_readlane_b32 s30, v252, 60
	v_readlane_b32 s31, v252, 61
	s_waitcnt vmcnt(6)
	v_pk_mul_f32 v[6:7], v[62:63], v[6:7] op_sel_hi:[0,1]
	s_waitcnt vmcnt(5)
	v_pk_mul_f32 v[10:11], v[62:63], v[10:11] op_sel_hi:[0,1]
	s_waitcnt vmcnt(4)
	v_pk_mul_f32 v[14:15], v[62:63], v[14:15] op_sel_hi:[0,1]
	s_waitcnt lgkmcnt(0)
	v_pk_fma_f32 v[2:3], v[2:3], s[18:19], v[14:15] op_sel_hi:[1,0,1]
	v_pk_mul_f32 v[18:19], v[62:63], v[18:19] op_sel_hi:[0,1]
	s_waitcnt vmcnt(3)
	v_pk_mul_f32 v[14:15], v[22:23], v[2:3]
	v_pk_mul_f32 v[2:3], v[62:63], v[16:17] op_sel_hi:[0,1]
	v_pk_fma_f32 v[2:3], v[4:5], s[18:19], v[2:3] op_sel_hi:[1,0,1]
	v_add_co_u32_e32 v22, vcc, s10, v58
	v_pk_mul_f32 v[16:17], v[24:25], v[2:3]
	ds_read2_b64 v[2:5], v63 offset0:2 offset1:3
	v_addc_co_u32_e32 v23, vcc, 0, v59, vcc
	global_store_dwordx4 v[22:23], v[14:17], off
	s_waitcnt lgkmcnt(0)
	v_pk_fma_f32 v[2:3], v[2:3], s[18:19], v[10:11] op_sel_hi:[1,0,1]
	s_waitcnt vmcnt(1)
	v_pk_mul_f32 v[10:11], v[34:35], v[2:3]
	v_pk_mul_f32 v[2:3], v[62:63], v[12:13] op_sel_hi:[0,1]
	v_pk_fma_f32 v[2:3], v[4:5], s[18:19], v[2:3] op_sel_hi:[1,0,1]
	s_nop 0
	v_pk_mul_f32 v[12:13], v[36:37], v[2:3]
	ds_read2_b64 v[2:5], v63 offset0:4 offset1:5
	global_store_dwordx4 v[22:23], v[10:13], off offset:16
	s_waitcnt lgkmcnt(0)
	v_pk_fma_f32 v[2:3], v[2:3], s[18:19], v[6:7] op_sel_hi:[1,0,1]
	s_nop 0
	v_pk_mul_f32 v[6:7], v[30:31], v[2:3]
	v_pk_mul_f32 v[2:3], v[62:63], v[8:9] op_sel_hi:[0,1]
	v_pk_fma_f32 v[2:3], v[4:5], s[18:19], v[2:3] op_sel_hi:[1,0,1]
	s_nop 0
	v_pk_mul_f32 v[8:9], v[32:33], v[2:3]
	ds_read2_b64 v[2:5], v63 offset0:6 offset1:7
	global_store_dwordx4 v[22:23], v[6:9], off offset:32
	s_waitcnt lgkmcnt(0)
	v_pk_fma_f32 v[2:3], v[2:3], s[18:19], v[18:19] op_sel_hi:[1,0,1]
	v_pk_mul_f32 v[18:19], v[62:63], v[20:21] op_sel_hi:[0,1]
	v_pk_fma_f32 v[4:5], v[4:5], s[18:19], v[18:19] op_sel_hi:[1,0,1]
	v_pk_mul_f32 v[2:3], v[26:27], v[2:3]
	v_pk_mul_f32 v[4:5], v[28:29], v[4:5]
	global_store_dwordx4 v[22:23], v[2:5], off offset:48
	v_add_co_u32_e32 v22, vcc, s2, v58
	ds_read2_b64 v[18:21], v1 offset1:1
	s_nop 0
	v_addc_co_u32_e32 v23, vcc, 0, v59, vcc
	global_load_dwordx2 v[22:23], v[22:23], off
	v_add_co_u32_e32 v24, vcc, s0, v58
	s_mov_b32 s0, 0x38000
	s_nop 0
	v_addc_co_u32_e32 v25, vcc, 0, v59, vcc
	global_load_dwordx2 v[24:25], v[24:25], off
	s_waitcnt vmcnt(1)
	v_pk_mul_f32 v[22:23], v[62:63], v[22:23] op_sel_hi:[0,1]
	s_waitcnt lgkmcnt(0)
	v_pk_fma_f32 v[18:19], v[18:19], s[18:19], v[22:23] op_sel_hi:[1,0,1]
	s_waitcnt vmcnt(0)
	v_pk_mul_f32 v[64:65], v[24:25], v[18:19]
	v_add_co_u32_e32 v18, vcc, s0, v58
	s_mov_b32 s0, 12
	s_nop 0
	v_addc_co_u32_e32 v19, vcc, 0, v59, vcc
	global_store_dwordx2 v[18:19], v[64:65], off
	v_add_u32_e32 v18, 0x1001, v50
	v_ashrrev_i32_e32 v19, 31, v18
	v_lshl_add_u64 v[54:55], v[18:19], 3, s[56:57]
	global_load_dwordx4 v[22:25], v[54:55], off offset:32
	global_load_dwordx4 v[30:33], v[54:55], off offset:16
	global_load_dwordx4 v[38:41], v[54:55], off
	global_load_dwordx2 v[66:67], v[54:55], off offset:48
	v_add_co_u32_e32 v26, vcc, s65, v54
	v_lshl_add_u64 v[18:19], v[54:55], 0, s[12:13]
	s_nop 0
	v_addc_co_u32_e32 v27, vcc, 0, v55, vcc
	global_load_dwordx4 v[42:45], v[26:27], off
	s_nop 0
	global_load_dwordx4 v[26:29], v[18:19], off offset:32
	global_load_dwordx4 v[34:37], v[18:19], off offset:16
	global_load_dwordx2 v[68:69], v[18:19], off offset:48
	v_lshl_add_u64 v[56:57], v[54:55], 0, s[16:17]
	s_waitcnt vmcnt(7)
	v_pk_mul_f32 v[22:23], v[62:63], v[22:23] op_sel_hi:[0,1]
	s_waitcnt vmcnt(6)
	v_pk_mul_f32 v[30:31], v[62:63], v[30:31] op_sel_hi:[0,1]
	s_waitcnt vmcnt(5)
; DI void hyena_lat_item(const P& p, int l, int c, int bp, unsigned char* lds) {
;     ...
;       float2 y1v[16];
; #pragma unroll
;       for (int i = 0; i < 16; ++i) {
;         int n = (i >> 3) * 4096 + tid * 8 + (i & 7);
;         float2 cv = s[phys(n)], v = scr[n], x1 = scr[8192 + n];
;         y1v[i] = make_float2(x1.x * (cv.x * invN + v.x * bias), x1.y * (cv.y * invN + v.y * bias));
;         scr[24576 + n] = y1v[i];
;       }
;       __syncthreads();
; #pragma unroll
;       for (int i = 0; i < 16; ++i) { int n = (i >> 3) * 4096 + tid * 8 + (i & 7); s[phys(n)] = y1v[i]; s[phys(n + L)] = make_float2(0.f, 0.f); }
	v_pk_mul_f32 v[18:19], v[62:63], v[38:39] op_sel_hi:[0,1]
	v_add_u32_e32 v38, 0x8010, v53
	ds_read2_b64 v[72:75], v38 offset1:1
	v_pk_fma_f32 v[18:19], v[20:21], s[18:19], v[18:19] op_sel_hi:[1,0,1]
	v_pk_mul_f32 v[20:21], v[62:63], v[40:41] op_sel_hi:[0,1]
	v_add_co_u32_e32 v40, vcc, s10, v54
	s_waitcnt lgkmcnt(0)
	v_pk_fma_f32 v[20:21], v[72:73], s[18:19], v[20:21] op_sel_hi:[1,0,1]
	s_waitcnt vmcnt(3)
	v_pk_mul_f32 v[18:19], v[42:43], v[18:19]
	v_pk_mul_f32 v[20:21], v[44:45], v[20:21]
	v_addc_co_u32_e32 v41, vcc, 0, v55, vcc
	global_store_dwordx4 v[40:41], v[18:21], off
	v_add_u32_e32 v40, 0x1003, v50
	v_pk_fma_f32 v[30:31], v[74:75], s[18:19], v[30:31] op_sel_hi:[1,0,1]
	v_ashrrev_i32_e32 v41, 31, v40
	s_waitcnt vmcnt(2)
	v_pk_mul_f32 v[34:35], v[34:35], v[30:31]
	v_add_u32_e32 v30, 0x8020, v53
	v_lshl_add_u64 v[44:45], v[40:41], 3, s[56:57]
	ds_read2_b64 v[40:43], v30 offset1:1
	v_pk_mul_f32 v[32:33], v[62:63], v[32:33] op_sel_hi:[0,1]
	v_pk_mul_f32 v[24:25], v[62:63], v[24:25] op_sel_hi:[0,1]
	s_waitcnt lgkmcnt(0)
	v_pk_fma_f32 v[32:33], v[40:41], s[18:19], v[32:33] op_sel_hi:[1,0,1]
	s_nop 0
	v_pk_mul_f32 v[36:37], v[36:37], v[32:33]
	v_add_co_u32_e32 v32, vcc, s10, v44
	v_pk_fma_f32 v[22:23], v[42:43], s[18:19], v[22:23] op_sel_hi:[1,0,1]
	s_nop 0
	v_addc_co_u32_e32 v33, vcc, 0, v45, vcc
	global_store_dwordx4 v[32:33], v[34:37], off
	v_add_u32_e32 v32, 0x1005, v50
	v_ashrrev_i32_e32 v33, 31, v32
	v_lshl_add_u64 v[44:45], v[32:33], 3, s[56:57]
	v_add_u32_e32 v32, 0x8030, v53
	ds_read2_b64 v[40:43], v32 offset1:1
	v_pk_mul_f32 v[22:23], v[26:27], v[22:23]
	v_add_co_u32_e32 v26, vcc, s10, v44
	s_waitcnt lgkmcnt(0)
	v_pk_fma_f32 v[24:25], v[40:41], s[18:19], v[24:25] op_sel_hi:[1,0,1]
	s_nop 0
	v_pk_mul_f32 v[24:25], v[28:29], v[24:25]
	v_addc_co_u32_e32 v27, vcc, 0, v45, vcc
	global_store_dwordx4 v[26:27], v[22:25], off
	v_add_u32_e32 v26, 0x1007, v50
	v_ashrrev_i32_e32 v27, 31, v26
	v_lshl_add_u64 v[26:27], v[26:27], 3, s[56:57]
	v_pk_mul_f32 v[28:29], v[62:63], v[66:67] op_sel_hi:[0,1]
	v_pk_fma_f32 v[28:29], v[42:43], s[18:19], v[28:29] op_sel_hi:[1,0,1]
	v_add_co_u32_e32 v26, vcc, s10, v26
	s_waitcnt vmcnt(3)
	v_pk_mul_f32 v[28:29], v[68:69], v[28:29]
	v_addc_co_u32_e32 v27, vcc, 0, v27, vcc
	global_store_dwordx2 v[26:27], v[28:29], off
	s_barrier
	ds_write_b64 v63, v[14:15]
	v_add_u32_e32 v14, 0x2000, v50
	v_ashrrev_i32_e32 v15, 4, v14
	v_lshlrev_b32_e32 v15, 3, v15
	v_lshlrev_b32_e32 v14, 3, v14
	v_add3_u32 v14, 0, v15, v14
	ds_write_b64 v14, v[230:231]
	ds_write_b64 v63, v[16:17] offset:8
	v_add_u32_e32 v14, 0x2001, v50
	v_ashrrev_i32_e32 v15, 4, v14
	v_lshlrev_b32_e32 v15, 3, v15
	v_lshlrev_b32_e32 v14, 3, v14
	v_add3_u32 v14, 0, v15, v14
	ds_write_b64 v14, v[230:231]
	ds_write_b64 v63, v[10:11] offset:16
	v_add_u32_e32 v10, 0x2002, v50
	v_ashrrev_i32_e32 v11, 4, v10
	v_lshlrev_b32_e32 v11, 3, v11
	v_lshlrev_b32_e32 v10, 3, v10
	v_add3_u32 v10, 0, v11, v10
	ds_write_b64 v10, v[230:231]
	ds_write_b64 v63, v[12:13] offset:24
	v_add_u32_e32 v10, 0x2003, v50
	v_ashrrev_i32_e32 v11, 4, v10
	v_lshlrev_b32_e32 v11, 3, v11
	v_lshlrev_b32_e32 v10, 3, v10
	v_add3_u32 v10, 0, v11, v10
	ds_write_b64 v10, v[230:231]
	ds_write_b64 v63, v[6:7] offset:32
	v_add_u32_e32 v6, 0x2004, v50
	v_ashrrev_i32_e32 v7, 4, v6
	v_lshlrev_b32_e32 v7, 3, v7
	v_lshlrev_b32_e32 v6, 3, v6
	v_add3_u32 v6, 0, v7, v6
	ds_write_b64 v6, v[230:231]
	ds_write_b64 v63, v[8:9] offset:40
	v_add_u32_e32 v6, 0x2005, v50
	v_ashrrev_i32_e32 v7, 4, v6
	v_lshlrev_b32_e32 v7, 3, v7
	v_lshlrev_b32_e32 v6, 3, v6
	v_add3_u32 v6, 0, v7, v6
	ds_write_b64 v6, v[230:231]
	ds_write_b64 v63, v[2:3] offset:48
	v_add_u32_e32 v2, 0x2006, v50
	v_ashrrev_i32_e32 v3, 4, v2
	v_lshlrev_b32_e32 v3, 3, v3
	v_lshlrev_b32_e32 v2, 3, v2
	v_add3_u32 v2, 0, v3, v2
	ds_write_b64 v2, v[230:231]
	ds_write_b64 v63, v[4:5] offset:56
	v_add_u32_e32 v2, 0x2007, v50
	v_ashrrev_i32_e32 v3, 4, v2
	v_lshlrev_b32_e32 v3, 3, v3
	v_lshlrev_b32_e32 v2, 3, v2
	v_add3_u32 v2, 0, v3, v2
	ds_write_b64 v2, v[230:231]
	ds_write_b64 v53, v[64:65] offset:32768
	v_add_u32_e32 v2, 0x3000, v50
	v_ashrrev_i32_e32 v3, 4, v2
	v_lshlrev_b32_e32 v3, 3, v3
	v_lshlrev_b32_e32 v2, 3, v2
	v_add3_u32 v2, 0, v3, v2
	ds_write_b64 v2, v[230:231]
	ds_write_b64 v53, v[18:19] offset:32776
	v_add_u32_e32 v2, 0x3001, v50
	v_ashrrev_i32_e32 v3, 4, v2
	v_lshlrev_b32_e32 v3, 3, v3
	v_lshlrev_b32_e32 v2, 3, v2
	v_add3_u32 v2, 0, v3, v2
	ds_write_b64 v2, v[230:231]
	ds_write_b64 v53, v[20:21] offset:32784
	v_add_u32_e32 v2, 0x3002, v50
	v_ashrrev_i32_e32 v3, 4, v2
	v_lshlrev_b32_e32 v3, 3, v3
	v_lshlrev_b32_e32 v2, 3, v2
	v_add3_u32 v2, 0, v3, v2
	ds_write_b64 v2, v[230:231]
	ds_write_b64 v53, v[34:35] offset:32792
	v_add_u32_e32 v2, 0x3003, v50
	v_ashrrev_i32_e32 v3, 4, v2
	v_lshlrev_b32_e32 v3, 3, v3
	v_lshlrev_b32_e32 v2, 3, v2
	v_add3_u32 v2, 0, v3, v2
	ds_write_b64 v2, v[230:231]
	ds_write_b64 v53, v[36:37] offset:32800
	v_add_u32_e32 v2, 0x3004, v50
	v_ashrrev_i32_e32 v3, 4, v2
	v_lshlrev_b32_e32 v3, 3, v3
	v_lshlrev_b32_e32 v2, 3, v2
	v_add3_u32 v2, 0, v3, v2
	ds_write_b64 v2, v[230:231]
	ds_write_b64 v53, v[22:23] offset:32808
	v_add_u32_e32 v2, 0x3005, v50
	v_ashrrev_i32_e32 v3, 4, v2
	v_lshlrev_b32_e32 v3, 3, v3
	v_lshlrev_b32_e32 v2, 3, v2
	v_add3_u32 v2, 0, v3, v2
	ds_write_b64 v2, v[230:231]
	ds_write_b64 v53, v[24:25] offset:32816
	v_add_u32_e32 v2, 0x3006, v50
	v_ashrrev_i32_e32 v3, 4, v2
	v_lshlrev_b32_e32 v3, 3, v3
	v_lshlrev_b32_e32 v2, 3, v2
	v_add3_u32 v2, 0, v3, v2
	ds_write_b64 v2, v[230:231]
	ds_write_b64 v53, v[28:29] offset:32824
	v_add_u32_e32 v2, 0x3007, v50
	v_ashrrev_i32_e32 v3, 4, v2
	v_lshlrev_b32_e32 v3, 3, v3
	v_lshlrev_b32_e32 v2, 3, v2
	v_add3_u32 v2, 0, v3, v2
	ds_write_b64 v2, v[230:231]
	v_mov_b32_e32 v2, v215

; DI float sin_t(float turns) { return __builtin_amdgcn_sinf(__builtin_amdgcn_fractf(turns)); }
; DI float cos_t(float turns) { return __builtin_amdgcn_cosf(__builtin_amdgcn_fractf(turns)); }
; DI float2 cmul(float2 a, float2 b) { return make_float2(a.x * b.x - a.y * b.y, a.x * b.y + a.y * b.x); }
; template <int N, bool INV>
; DI void fft_lds(float2* s) {
;     ...
;     for (int lq = 0; (1 << lq) <= top; lq += 2) {
;       const int q = 1 << lq;
;       __syncthreads();
;       const float inv4q = 1.0f / (float)(4 * q);
; #pragma unroll 4
;       for (int it = 0; it < N / 4 / NT; ++it) {
;         int idx = tid + it * NT;
;         int j = idx & (q - 1), blk = idx >> lq;
;         int p0 = blk * 4 * q + j;
;         float f = (float)j * inv4q;
;         float2 t1 = make_float2(cos_t(f), sin_t(f));
;         float2 t2 = cmul(t1, t1);
;         float2 x0 = s[phys(p0)], x1 = s[phys(p0 + q)], x2 = s[phys(p0 + 2 * q)], x3 = s[phys(p0 + 3 * q)];
;         float2 b = cmul(x1, t2);
;         float2 a0 = make_float2(x0.x + b.x, x0.y + b.y), a1 = make_float2(x0.x - b.x, x0.y - b.y);
;         b = cmul(x3, t2);
;         float2 a2 = make_float2(x2.x + b.x, x2.y + b.y), a3 = make_float2(x2.x - b.x, x2.y - b.y);
;         b = cmul(a2, t1);
;         s[phys(p0)] = make_float2(a0.x + b.x, a0.y + b.y);
;         s[phys(p0 + 2 * q)] = make_float2(a0.x - b.x, a0.y - b.y);
;         float2 c3 = cmul(a3, t1);
;         b = make_float2(-c3.y, c3.x);
;         s[phys(p0 + q)] = make_float2(a1.x + b.x, a1.y + b.y);
;         s[phys(p0 + 3 * q)] = make_float2(a1.x - b.x, a1.y - b.y);
;       }
.LBB0_500:
	s_lshl_b32 s5, s0, 23
	s_lshl_b32 s4, 4, s0
	s_sub_i32 s5, 0x3e800000, s5
	s_add_i32 s10, s1, -1
	s_mov_b32 s11, 0
	s_waitcnt lgkmcnt(0)
	s_barrier
	s_sub_i32 s32, s0, 4
	s_lshl_b32 s32, 0x88, s32
	s_cmp_lt_u32 s0, 4
	s_cbranch_scc0 .Lfft_fast_3
.LBB0_501:
	v_add_u32_e32 v3, s11, v2
	v_ashrrev_i32_e32 v4, s0, v3
	v_and_b32_e32 v9, s10, v3
	v_lshlrev_b32_e32 v10, 2, v4
	v_lshl_add_u32 v11, v10, s0, v9
	v_cvt_f32_u32_e32 v4, v9
	v_ashrrev_i32_e32 v12, 4, v11
	v_add_lshl_u32 v22, v12, v11, 3
	v_add_u32_e32 v11, s1, v11
	v_ashrrev_i32_e32 v12, 4, v11
	v_add_lshl_u32 v23, v12, v11, 3
	v_mul_f32_e32 v4, s5, v4
	v_or_b32_e32 v11, 2, v10
	v_or_b32_e32 v10, 3, v10
	v_fract_f32_e32 v5, v4
	v_lshl_add_u32 v11, v11, s0, v9
	v_lshl_add_u32 v9, v10, s0, v9
	v_cos_f32_e32 v4, v5
	v_sin_f32_e32 v5, v5
	v_ashrrev_i32_e32 v12, 4, v11
	v_ashrrev_i32_e32 v10, 4, v9
	v_add_lshl_u32 v24, v12, v11, 3
	v_lshlrev_b32_e32 v10, 3, v10
	v_lshlrev_b32_e32 v9, 3, v9
	v_add3_u32 v25, 0, v10, v9
	ds_read_b64 v[10:11], v22
	ds_read_b64 v[12:13], v23
	ds_read_b64 v[14:15], v24
	ds_read_b64 v[16:17], v25
	v_mul_f32_e32 v8, v4, v5
	v_pk_mul_f32 v[6:7], v[4:5], v[4:5]
	v_add_f32_e32 v8, v8, v8
	s_waitcnt lgkmcnt(2)
	v_pk_mul_f32 v[18:19], v[12:13], v[8:9] op_sel_hi:[1,0]
	v_pk_add_f32 v[6:7], v[6:7], v[6:7] op_sel:[0,1] op_sel_hi:[0,1] neg_lo:[0,1] neg_hi:[0,1]
	v_pk_fma_f32 v[20:21], v[12:13], v[6:7], v[18:19] op_sel:[0,0,1] op_sel_hi:[1,1,0] neg_lo:[0,0,1] neg_hi:[0,0,1]
	v_pk_fma_f32 v[12:13], v[12:13], v[6:7], v[18:19] op_sel:[0,0,1] op_sel_hi:[1,1,0]
	s_waitcnt lgkmcnt(0)
	v_pk_mul_f32 v[6:7], v[16:17], v[6:7]
	v_mov_b32_e32 v21, v13
	v_pk_fma_f32 v[18:19], v[16:17], v[8:9], v[6:7] op_sel:[0,0,1] op_sel_hi:[1,1,0]
	v_pk_fma_f32 v[6:7], v[16:17], v[8:9], v[6:7] op_sel:[0,0,1] op_sel_hi:[1,0,0] neg_lo:[1,0,0] neg_hi:[1,0,0]
	v_pk_add_f32 v[12:13], v[10:11], v[20:21] neg_lo:[0,1] neg_hi:[0,1]
	v_mov_b32_e32 v19, v7
	v_pk_add_f32 v[8:9], v[10:11], v[20:21]
	v_pk_add_f32 v[10:11], v[14:15], v[18:19] op_sel:[1,0] op_sel_hi:[0,1]
	v_pk_add_f32 v[6:7], v[14:15], v[18:19] op_sel:[1,0] op_sel_hi:[0,1] neg_lo:[0,1] neg_hi:[0,1]
	v_mov_b32_e32 v14, v5
	v_mov_b32_e32 v16, v5
	v_pk_mul_f32 v[18:19], v[4:5], v[10:11] op_sel_hi:[0,1]
	v_pk_fma_f32 v[14:15], v[14:15], v[10:11], v[18:19] op_sel:[0,0,1] op_sel_hi:[1,1,0] neg_lo:[1,0,0] neg_hi:[1,0,0]
	v_pk_fma_f32 v[10:11], v[16:17], v[10:11], v[18:19] op_sel:[0,0,1] op_sel_hi:[0,1,0]
	v_mov_b32_e32 v15, v11
	v_pk_add_f32 v[10:11], v[8:9], v[14:15]
	v_pk_add_f32 v[8:9], v[8:9], v[14:15] neg_lo:[0,1] neg_hi:[0,1]
	ds_write_b64 v22, v[10:11]
	ds_write_b64 v24, v[8:9]
	v_pk_mul_f32 v[8:9], v[16:17], v[6:7] op_sel_hi:[0,1]
	v_pk_fma_f32 v[10:11], v[4:5], v[6:7], v[8:9] op_sel:[0,0,1] op_sel_hi:[1,1,0]
	v_pk_fma_f32 v[4:5], v[4:5], v[6:7], v[8:9] op_sel:[0,0,1] op_sel_hi:[0,1,0] neg_lo:[0,0,1] neg_hi:[0,0,1]
	v_mov_b32_e32 v11, v5
	v_pk_add_f32 v[4:5], v[12:13], v[10:11] neg_lo:[0,1] neg_hi:[0,1]
	v_pk_add_f32 v[6:7], v[12:13], v[10:11]
	v_mov_b32_e32 v8, v4
	v_mov_b32_e32 v9, v7
	v_add_u32_e32 v4, 0x200, v3
	ds_write_b64 v23, v[8:9]
	v_and_b32_e32 v9, s10, v4
	v_ashrrev_i32_e32 v4, s0, v4
	v_lshlrev_b32_e32 v10, 2, v4
	v_lshl_add_u32 v11, v10, s0, v9
	v_cvt_f32_u32_e32 v4, v9
	v_ashrrev_i32_e32 v12, 4, v11
	v_add_lshl_u32 v22, v12, v11, 3
	v_add_u32_e32 v11, s1, v11
	v_ashrrev_i32_e32 v12, 4, v11
	v_add_lshl_u32 v23, v12, v11, 3
	v_mul_f32_e32 v4, s5, v4
	v_or_b32_e32 v11, 2, v10
	v_or_b32_e32 v10, 3, v10
	v_mov_b32_e32 v7, v5
	v_fract_f32_e32 v5, v4
	v_lshl_add_u32 v11, v11, s0, v9
	v_lshl_add_u32 v9, v10, s0, v9
	v_cos_f32_e32 v4, v5
	v_sin_f32_e32 v5, v5
	v_ashrrev_i32_e32 v12, 4, v11
	v_ashrrev_i32_e32 v10, 4, v9
	ds_write_b64 v25, v[6:7]
	v_add_lshl_u32 v24, v12, v11, 3
	v_lshlrev_b32_e32 v10, 3, v10
	v_lshlrev_b32_e32 v9, 3, v9
	v_add3_u32 v25, 0, v10, v9
	ds_read_b64 v[10:11], v22
	ds_read_b64 v[12:13], v23
	ds_read_b64 v[14:15], v24
	ds_read_b64 v[16:17], v25
	v_mul_f32_e32 v8, v4, v5
	v_pk_mul_f32 v[6:7], v[4:5], v[4:5]
	v_add_f32_e32 v8, v8, v8
	s_waitcnt lgkmcnt(2)
	v_pk_mul_f32 v[18:19], v[12:13], v[8:9] op_sel_hi:[1,0]
	v_pk_add_f32 v[6:7], v[6:7], v[6:7] op_sel:[0,1] op_sel_hi:[0,1] neg_lo:[0,1] neg_hi:[0,1]
	v_pk_fma_f32 v[20:21], v[12:13], v[6:7], v[18:19] op_sel:[0,0,1] op_sel_hi:[1,1,0] neg_lo:[0,0,1] neg_hi:[0,0,1]
	v_pk_fma_f32 v[12:13], v[12:13], v[6:7], v[18:19] op_sel:[0,0,1] op_sel_hi:[1,1,0]
	s_waitcnt lgkmcnt(0)
; DI float sin_t(float turns) { return __builtin_amdgcn_sinf(__builtin_amdgcn_fractf(turns)); }
; DI float cos_t(float turns) { return __builtin_amdgcn_cosf(__builtin_amdgcn_fractf(turns)); }
; DI float2 cmul(float2 a, float2 b) { return make_float2(a.x * b.x - a.y * b.y, a.x * b.y + a.y * b.x); }
; template <int N, bool INV>
; DI void fft_lds(float2* s) {
;     ...
; #pragma unroll 4
;       for (int it = 0; it < N / 4 / NT; ++it) {
;         int idx = tid + it * NT;
;         int j = idx & (q - 1), blk = idx >> lq;
;         int p0 = blk * 4 * q + j;
;         float f = (float)j * inv4q;
;         float2 t1 = make_float2(cos_t(f), sin_t(f));
;         float2 t2 = cmul(t1, t1);
;         float2 x0 = s[phys(p0)], x1 = s[phys(p0 + q)], x2 = s[phys(p0 + 2 * q)], x3 = s[phys(p0 + 3 * q)];
;         float2 b = cmul(x1, t2);
;         float2 a0 = make_float2(x0.x + b.x, x0.y + b.y), a1 = make_float2(x0.x - b.x, x0.y - b.y);
;         b = cmul(x3, t2);
;         float2 a2 = make_float2(x2.x + b.x, x2.y + b.y), a3 = make_float2(x2.x - b.x, x2.y - b.y);
;         b = cmul(a2, t1);
;         s[phys(p0)] = make_float2(a0.x + b.x, a0.y + b.y);
;         s[phys(p0 + 2 * q)] = make_float2(a0.x - b.x, a0.y - b.y);
;         float2 c3 = cmul(a3, t1);
;         b = make_float2(-c3.y, c3.x);
;         s[phys(p0 + q)] = make_float2(a1.x + b.x, a1.y + b.y);
;         s[phys(p0 + 3 * q)] = make_float2(a1.x - b.x, a1.y - b.y);
;       }
	v_pk_mul_f32 v[6:7], v[16:17], v[6:7]
	v_mov_b32_e32 v21, v13
	v_pk_fma_f32 v[18:19], v[16:17], v[8:9], v[6:7] op_sel:[0,0,1] op_sel_hi:[1,1,0]
	v_pk_fma_f32 v[6:7], v[16:17], v[8:9], v[6:7] op_sel:[0,0,1] op_sel_hi:[1,0,0] neg_lo:[1,0,0] neg_hi:[1,0,0]
	v_pk_add_f32 v[12:13], v[10:11], v[20:21] neg_lo:[0,1] neg_hi:[0,1]
	v_mov_b32_e32 v19, v7
	v_pk_add_f32 v[8:9], v[10:11], v[20:21]
	v_pk_add_f32 v[10:11], v[14:15], v[18:19] op_sel:[1,0] op_sel_hi:[0,1]
	v_pk_add_f32 v[6:7], v[14:15], v[18:19] op_sel:[1,0] op_sel_hi:[0,1] neg_lo:[0,1] neg_hi:[0,1]
	v_mov_b32_e32 v14, v5
	v_mov_b32_e32 v16, v5
	v_pk_mul_f32 v[18:19], v[4:5], v[10:11] op_sel_hi:[0,1]
	v_pk_fma_f32 v[14:15], v[14:15], v[10:11], v[18:19] op_sel:[0,0,1] op_sel_hi:[1,1,0] neg_lo:[1,0,0] neg_hi:[1,0,0]
	v_pk_fma_f32 v[10:11], v[16:17], v[10:11], v[18:19] op_sel:[0,0,1] op_sel_hi:[0,1,0]
	v_mov_b32_e32 v15, v11
	v_pk_add_f32 v[10:11], v[8:9], v[14:15]
	v_pk_add_f32 v[8:9], v[8:9], v[14:15] neg_lo:[0,1] neg_hi:[0,1]
	ds_write_b64 v22, v[10:11]
	ds_write_b64 v24, v[8:9]
	v_pk_mul_f32 v[8:9], v[16:17], v[6:7] op_sel_hi:[0,1]
	v_pk_fma_f32 v[10:11], v[4:5], v[6:7], v[8:9] op_sel:[0,0,1] op_sel_hi:[1,1,0]
	v_pk_fma_f32 v[4:5], v[4:5], v[6:7], v[8:9] op_sel:[0,0,1] op_sel_hi:[0,1,0] neg_lo:[0,0,1] neg_hi:[0,0,1]
	v_mov_b32_e32 v11, v5
	v_pk_add_f32 v[4:5], v[12:13], v[10:11] neg_lo:[0,1] neg_hi:[0,1]
	v_pk_add_f32 v[6:7], v[12:13], v[10:11]
	v_mov_b32_e32 v8, v4
	v_mov_b32_e32 v9, v7
	v_add_u32_e32 v4, 0x400, v3
	ds_write_b64 v23, v[8:9]
	v_and_b32_e32 v9, s10, v4
	v_ashrrev_i32_e32 v4, s0, v4
	v_lshlrev_b32_e32 v10, 2, v4
	v_lshl_add_u32 v11, v10, s0, v9
	v_cvt_f32_u32_e32 v4, v9
	v_ashrrev_i32_e32 v12, 4, v11
	v_add_lshl_u32 v22, v12, v11, 3
	v_add_u32_e32 v11, s1, v11
	v_ashrrev_i32_e32 v12, 4, v11
	v_add_lshl_u32 v23, v12, v11, 3
	v_mul_f32_e32 v4, s5, v4
	v_or_b32_e32 v11, 2, v10
	v_or_b32_e32 v10, 3, v10
	v_mov_b32_e32 v7, v5
	v_fract_f32_e32 v5, v4
	v_lshl_add_u32 v11, v11, s0, v9
	v_lshl_add_u32 v9, v10, s0, v9
	v_cos_f32_e32 v4, v5
	v_sin_f32_e32 v5, v5
	v_ashrrev_i32_e32 v12, 4, v11
	v_ashrrev_i32_e32 v10, 4, v9
	ds_write_b64 v25, v[6:7]
	v_add_lshl_u32 v24, v12, v11, 3
	v_lshlrev_b32_e32 v10, 3, v10
	v_lshlrev_b32_e32 v9, 3, v9
	v_add3_u32 v25, 0, v10, v9
	ds_read_b64 v[10:11], v22
	ds_read_b64 v[12:13], v23
	ds_read_b64 v[14:15], v24
	ds_read_b64 v[16:17], v25
	v_mul_f32_e32 v8, v4, v5
	v_pk_mul_f32 v[6:7], v[4:5], v[4:5]
	v_add_f32_e32 v8, v8, v8
	s_waitcnt lgkmcnt(2)
	v_pk_mul_f32 v[18:19], v[12:13], v[8:9] op_sel_hi:[1,0]
	v_pk_add_f32 v[6:7], v[6:7], v[6:7] op_sel:[0,1] op_sel_hi:[0,1] neg_lo:[0,1] neg_hi:[0,1]
	v_pk_fma_f32 v[20:21], v[12:13], v[6:7], v[18:19] op_sel:[0,0,1] op_sel_hi:[1,1,0] neg_lo:[0,0,1] neg_hi:[0,0,1]
	v_pk_fma_f32 v[12:13], v[12:13], v[6:7], v[18:19] op_sel:[0,0,1] op_sel_hi:[1,1,0]
	s_waitcnt lgkmcnt(0)
	v_pk_mul_f32 v[6:7], v[16:17], v[6:7]
	v_mov_b32_e32 v21, v13
	v_pk_fma_f32 v[18:19], v[16:17], v[8:9], v[6:7] op_sel:[0,0,1] op_sel_hi:[1,1,0]
	v_pk_fma_f32 v[6:7], v[16:17], v[8:9], v[6:7] op_sel:[0,0,1] op_sel_hi:[1,0,0] neg_lo:[1,0,0] neg_hi:[1,0,0]
	v_pk_add_f32 v[12:13], v[10:11], v[20:21] neg_lo:[0,1] neg_hi:[0,1]
	v_mov_b32_e32 v19, v7
	v_pk_add_f32 v[8:9], v[10:11], v[20:21]
	v_pk_add_f32 v[10:11], v[14:15], v[18:19] op_sel:[1,0] op_sel_hi:[0,1]
	v_pk_add_f32 v[6:7], v[14:15], v[18:19] op_sel:[1,0] op_sel_hi:[0,1] neg_lo:[0,1] neg_hi:[0,1]
	v_mov_b32_e32 v14, v5
	v_mov_b32_e32 v16, v5
	v_pk_mul_f32 v[18:19], v[4:5], v[10:11] op_sel_hi:[0,1]
	v_pk_fma_f32 v[14:15], v[14:15], v[10:11], v[18:19] op_sel:[0,0,1] op_sel_hi:[1,1,0] neg_lo:[1,0,0] neg_hi:[1,0,0]
	v_pk_fma_f32 v[10:11], v[16:17], v[10:11], v[18:19] op_sel:[0,0,1] op_sel_hi:[0,1,0]
	v_mov_b32_e32 v15, v11
	v_pk_add_f32 v[10:11], v[8:9], v[14:15]
	v_pk_add_f32 v[8:9], v[8:9], v[14:15] neg_lo:[0,1] neg_hi:[0,1]
	ds_write_b64 v22, v[10:11]
	ds_write_b64 v24, v[8:9]
	v_pk_mul_f32 v[8:9], v[16:17], v[6:7] op_sel_hi:[0,1]
	v_pk_fma_f32 v[10:11], v[4:5], v[6:7], v[8:9] op_sel:[0,0,1] op_sel_hi:[1,1,0]
	v_pk_fma_f32 v[4:5], v[4:5], v[6:7], v[8:9] op_sel:[0,0,1] op_sel_hi:[0,1,0] neg_lo:[0,0,1] neg_hi:[0,0,1]
	v_mov_b32_e32 v11, v5
	v_pk_add_f32 v[4:5], v[12:13], v[10:11] neg_lo:[0,1] neg_hi:[0,1]
	v_pk_add_f32 v[6:7], v[12:13], v[10:11]
	v_mov_b32_e32 v8, v4
	v_mov_b32_e32 v9, v7
	v_add_u32_e32 v3, 0x600, v3
	ds_write_b64 v23, v[8:9]
	v_and_b32_e32 v9, s10, v3
	v_ashrrev_i32_e32 v3, s0, v3
	v_lshlrev_b32_e32 v3, 2, v3
	v_lshl_add_u32 v10, v3, s0, v9
	v_cvt_f32_u32_e32 v4, v9
	v_ashrrev_i32_e32 v11, 4, v10
	v_add_lshl_u32 v22, v11, v10, 3
	v_add_u32_e32 v10, s1, v10
	v_ashrrev_i32_e32 v11, 4, v10
	v_add_lshl_u32 v23, v11, v10, 3
	v_mul_f32_e32 v4, s5, v4
	v_or_b32_e32 v10, 2, v3
	v_or_b32_e32 v3, 3, v3
	v_mov_b32_e32 v7, v5
	v_fract_f32_e32 v5, v4
	v_lshl_add_u32 v10, v10, s0, v9
	v_lshl_add_u32 v3, v3, s0, v9
	v_cos_f32_e32 v4, v5
	v_sin_f32_e32 v5, v5
	v_ashrrev_i32_e32 v11, 4, v10
	v_ashrrev_i32_e32 v9, 4, v3
	ds_write_b64 v25, v[6:7]
	v_add_lshl_u32 v24, v11, v10, 3
	v_lshlrev_b32_e32 v9, 3, v9
	v_lshlrev_b32_e32 v3, 3, v3
	v_add3_u32 v3, 0, v9, v3
	ds_read_b64 v[10:11], v22
	ds_read_b64 v[12:13], v23
	ds_read_b64 v[14:15], v24
	ds_read_b64 v[16:17], v3
	v_mul_f32_e32 v8, v4, v5
	v_pk_mul_f32 v[6:7], v[4:5], v[4:5]
	v_add_f32_e32 v8, v8, v8
	s_waitcnt lgkmcnt(2)
	v_pk_mul_f32 v[18:19], v[12:13], v[8:9] op_sel_hi:[1,0]
	v_pk_add_f32 v[6:7], v[6:7], v[6:7] op_sel:[0,1] op_sel_hi:[0,1] neg_lo:[0,1] neg_hi:[0,1]
	v_pk_fma_f32 v[20:21], v[12:13], v[6:7], v[18:19] op_sel:[0,0,1] op_sel_hi:[1,1,0] neg_lo:[0,0,1] neg_hi:[0,0,1]
	v_pk_fma_f32 v[12:13], v[12:13], v[6:7], v[18:19] op_sel:[0,0,1] op_sel_hi:[1,1,0]
	s_waitcnt lgkmcnt(0)
; DI float sin_t(float turns) { return __builtin_amdgcn_sinf(__builtin_amdgcn_fractf(turns)); }
; DI float cos_t(float turns) { return __builtin_amdgcn_cosf(__builtin_amdgcn_fractf(turns)); }
; DI float2 cmul(float2 a, float2 b) { return make_float2(a.x * b.x - a.y * b.y, a.x * b.y + a.y * b.x); }
; template <int N, bool INV>
; DI void fft_lds(float2* s) {
;     ...
;     for (int lq = 0; (1 << lq) <= top; lq += 2) {
;       const int q = 1 << lq;
;       __syncthreads();
;       const float inv4q = 1.0f / (float)(4 * q);
; #pragma unroll 4
;       for (int it = 0; it < N / 4 / NT; ++it) {
;         int idx = tid + it * NT;
;         int j = idx & (q - 1), blk = idx >> lq;
;         int p0 = blk * 4 * q + j;
;         float f = (float)j * inv4q;
;         float2 t1 = make_float2(cos_t(f), sin_t(f));
;         float2 t2 = cmul(t1, t1);
;         float2 x0 = s[phys(p0)], x1 = s[phys(p0 + q)], x2 = s[phys(p0 + 2 * q)], x3 = s[phys(p0 + 3 * q)];
;         float2 b = cmul(x1, t2);
;         float2 a0 = make_float2(x0.x + b.x, x0.y + b.y), a1 = make_float2(x0.x - b.x, x0.y - b.y);
;         b = cmul(x3, t2);
;         float2 a2 = make_float2(x2.x + b.x, x2.y + b.y), a3 = make_float2(x2.x - b.x, x2.y - b.y);
;         b = cmul(a2, t1);
;         s[phys(p0)] = make_float2(a0.x + b.x, a0.y + b.y);
;         s[phys(p0 + 2 * q)] = make_float2(a0.x - b.x, a0.y - b.y);
;         float2 c3 = cmul(a3, t1);
;         b = make_float2(-c3.y, c3.x);
;         s[phys(p0 + q)] = make_float2(a1.x + b.x, a1.y + b.y);
;         s[phys(p0 + 3 * q)] = make_float2(a1.x - b.x, a1.y - b.y);
;       }
;     }
	v_pk_mul_f32 v[6:7], v[16:17], v[6:7]
	v_mov_b32_e32 v21, v13
	v_pk_fma_f32 v[18:19], v[16:17], v[8:9], v[6:7] op_sel:[0,0,1] op_sel_hi:[1,1,0]
	v_pk_fma_f32 v[6:7], v[16:17], v[8:9], v[6:7] op_sel:[0,0,1] op_sel_hi:[1,0,0] neg_lo:[1,0,0] neg_hi:[1,0,0]
	v_pk_add_f32 v[12:13], v[10:11], v[20:21] neg_lo:[0,1] neg_hi:[0,1]
	v_mov_b32_e32 v19, v7
	v_pk_add_f32 v[8:9], v[10:11], v[20:21]
	v_pk_add_f32 v[10:11], v[14:15], v[18:19] op_sel:[1,0] op_sel_hi:[0,1]
	v_pk_add_f32 v[6:7], v[14:15], v[18:19] op_sel:[1,0] op_sel_hi:[0,1] neg_lo:[0,1] neg_hi:[0,1]
	v_mov_b32_e32 v14, v5
	v_mov_b32_e32 v16, v5
	v_pk_mul_f32 v[18:19], v[4:5], v[10:11] op_sel_hi:[0,1]
	v_pk_fma_f32 v[14:15], v[14:15], v[10:11], v[18:19] op_sel:[0,0,1] op_sel_hi:[1,1,0] neg_lo:[1,0,0] neg_hi:[1,0,0]
	v_pk_fma_f32 v[10:11], v[16:17], v[10:11], v[18:19] op_sel:[0,0,1] op_sel_hi:[0,1,0]
	v_mov_b32_e32 v15, v11
	v_pk_add_f32 v[10:11], v[8:9], v[14:15]
	v_pk_add_f32 v[8:9], v[8:9], v[14:15] neg_lo:[0,1] neg_hi:[0,1]
	ds_write_b64 v22, v[10:11]
	ds_write_b64 v24, v[8:9]
	v_pk_mul_f32 v[8:9], v[16:17], v[6:7] op_sel_hi:[0,1]
	v_pk_fma_f32 v[10:11], v[4:5], v[6:7], v[8:9] op_sel:[0,0,1] op_sel_hi:[1,1,0]
	v_pk_fma_f32 v[4:5], v[4:5], v[6:7], v[8:9] op_sel:[0,0,1] op_sel_hi:[0,1,0] neg_lo:[0,0,1] neg_hi:[0,0,1]
	v_mov_b32_e32 v11, v5
	v_pk_add_f32 v[4:5], v[12:13], v[10:11] neg_lo:[0,1] neg_hi:[0,1]
	v_pk_add_f32 v[6:7], v[12:13], v[10:11]
	s_addk_i32 s11, 0x800
	v_mov_b32_e32 v8, v4
	v_mov_b32_e32 v9, v7
	v_mov_b32_e32 v7, v5
	s_cmpk_lg_i32 s11, 0x1000
	ds_write_b64 v23, v[8:9]
	ds_write_b64 v3, v[6:7]
	s_cbranch_scc1 .LBB0_501
	s_branch .Lfft_done_3
.Lfft_fast_3:
	v_add_u32_e32 v3, s11, v2
	v_ashrrev_i32_e32 v4, s0, v3
	v_and_b32_e32 v9, s10, v3
	v_lshlrev_b32_e32 v10, 2, v4
	v_lshl_add_u32 v11, v10, s0, v9
	v_cvt_f32_u32_e32 v4, v9
	v_ashrrev_i32_e32 v12, 4, v11
	v_add_lshl_u32 v22, v12, v11, 3
	v_mul_f32_e32 v4, s5, v4
	v_fract_f32_e32 v5, v4
	v_cos_f32_e32 v4, v5
	v_sin_f32_e32 v5, v5
	v_add_u32_e32 v23, s32, v22
	v_add_u32_e32 v24, s32, v23
	v_add_u32_e32 v25, s32, v24
	ds_read_b64 v[10:11], v22
	ds_read_b64 v[12:13], v23
	ds_read_b64 v[14:15], v24
	ds_read_b64 v[16:17], v25
	v_mul_f32_e32 v8, v4, v5
	v_pk_mul_f32 v[6:7], v[4:5], v[4:5]
	v_add_f32_e32 v8, v8, v8
	s_waitcnt lgkmcnt(2)
	v_pk_mul_f32 v[18:19], v[12:13], v[8:9] op_sel_hi:[1,0]
	v_pk_add_f32 v[6:7], v[6:7], v[6:7] op_sel:[0,1] op_sel_hi:[0,1] neg_lo:[0,1] neg_hi:[0,1]
	v_pk_fma_f32 v[20:21], v[12:13], v[6:7], v[18:19] op_sel:[0,0,1] op_sel_hi:[1,1,0] neg_lo:[0,0,1] neg_hi:[0,0,1]
	v_pk_fma_f32 v[12:13], v[12:13], v[6:7], v[18:19] op_sel:[0,0,1] op_sel_hi:[1,1,0]
	s_waitcnt lgkmcnt(0)
	v_pk_mul_f32 v[6:7], v[16:17], v[6:7]
	v_mov_b32_e32 v21, v13
	v_pk_fma_f32 v[18:19], v[16:17], v[8:9], v[6:7] op_sel:[0,0,1] op_sel_hi:[1,1,0]
	v_pk_fma_f32 v[6:7], v[16:17], v[8:9], v[6:7] op_sel:[0,0,1] op_sel_hi:[1,0,0] neg_lo:[1,0,0] neg_hi:[1,0,0]
	v_pk_add_f32 v[12:13], v[10:11], v[20:21] neg_lo:[0,1] neg_hi:[0,1]
	v_mov_b32_e32 v19, v7
	v_pk_add_f32 v[8:9], v[10:11], v[20:21]
	v_pk_add_f32 v[10:11], v[14:15], v[18:19] op_sel:[1,0] op_sel_hi:[0,1]
	v_pk_add_f32 v[6:7], v[14:15], v[18:19] op_sel:[1,0] op_sel_hi:[0,1] neg_lo:[0,1] neg_hi:[0,1]
	v_mov_b32_e32 v14, v5
	v_mov_b32_e32 v16, v5
	v_pk_mul_f32 v[18:19], v[4:5], v[10:11] op_sel_hi:[0,1]
	v_pk_fma_f32 v[14:15], v[14:15], v[10:11], v[18:19] op_sel:[0,0,1] op_sel_hi:[1,1,0] neg_lo:[1,0,0] neg_hi:[1,0,0]
	v_pk_fma_f32 v[10:11], v[16:17], v[10:11], v[18:19] op_sel:[0,0,1] op_sel_hi:[0,1,0]
	v_mov_b32_e32 v15, v11
	v_pk_add_f32 v[10:11], v[8:9], v[14:15]
	v_pk_add_f32 v[8:9], v[8:9], v[14:15] neg_lo:[0,1] neg_hi:[0,1]
	ds_write_b64 v22, v[10:11]
	ds_write_b64 v24, v[8:9]
	v_pk_mul_f32 v[8:9], v[16:17], v[6:7] op_sel_hi:[0,1]
	v_pk_fma_f32 v[10:11], v[4:5], v[6:7], v[8:9] op_sel:[0,0,1] op_sel_hi:[1,1,0]
	v_pk_fma_f32 v[4:5], v[4:5], v[6:7], v[8:9] op_sel:[0,0,1] op_sel_hi:[0,1,0] neg_lo:[0,0,1] neg_hi:[0,0,1]
	v_mov_b32_e32 v11, v5
	v_pk_add_f32 v[4:5], v[12:13], v[10:11] neg_lo:[0,1] neg_hi:[0,1]
	v_pk_add_f32 v[6:7], v[12:13], v[10:11]
	v_mov_b32_e32 v8, v4
	v_mov_b32_e32 v9, v7
	v_add_u32_e32 v4, 0x200, v3
	ds_write_b64 v23, v[8:9]
	v_and_b32_e32 v9, s10, v4
	v_ashrrev_i32_e32 v4, s0, v4
	v_lshlrev_b32_e32 v10, 2, v4
	v_lshl_add_u32 v11, v10, s0, v9
	v_cvt_f32_u32_e32 v4, v9
	v_ashrrev_i32_e32 v12, 4, v11
	v_add_lshl_u32 v22, v12, v11, 3
	v_mul_f32_e32 v4, s5, v4
	v_mov_b32_e32 v7, v5
	v_fract_f32_e32 v5, v4
	v_cos_f32_e32 v4, v5
	v_sin_f32_e32 v5, v5
	ds_write_b64 v25, v[6:7]
	v_add_u32_e32 v23, s32, v22
	v_add_u32_e32 v24, s32, v23
	v_add_u32_e32 v25, s32, v24
	ds_read_b64 v[10:11], v22
	ds_read_b64 v[12:13], v23
	ds_read_b64 v[14:15], v24
	ds_read_b64 v[16:17], v25
	v_mul_f32_e32 v8, v4, v5
	v_pk_mul_f32 v[6:7], v[4:5], v[4:5]
	v_add_f32_e32 v8, v8, v8
	s_waitcnt lgkmcnt(2)
	v_pk_mul_f32 v[18:19], v[12:13], v[8:9] op_sel_hi:[1,0]
	v_pk_add_f32 v[6:7], v[6:7], v[6:7] op_sel:[0,1] op_sel_hi:[0,1] neg_lo:[0,1] neg_hi:[0,1]
	v_pk_fma_f32 v[20:21], v[12:13], v[6:7], v[18:19] op_sel:[0,0,1] op_sel_hi:[1,1,0] neg_lo:[0,0,1] neg_hi:[0,0,1]
	v_pk_fma_f32 v[12:13], v[12:13], v[6:7], v[18:19] op_sel:[0,0,1] op_sel_hi:[1,1,0]
	s_waitcnt lgkmcnt(0)
; DI float sin_t(float turns) { return __builtin_amdgcn_sinf(__builtin_amdgcn_fractf(turns)); }
; DI float cos_t(float turns) { return __builtin_amdgcn_cosf(__builtin_amdgcn_fractf(turns)); }
; DI float2 cmul(float2 a, float2 b) { return make_float2(a.x * b.x - a.y * b.y, a.x * b.y + a.y * b.x); }
; template <int N, bool INV>
; DI void fft_lds(float2* s) {
;     ...
;     for (int lq = 0; (1 << lq) <= top; lq += 2) {
;       const int q = 1 << lq;
;       __syncthreads();
;       const float inv4q = 1.0f / (float)(4 * q);
; #pragma unroll 4
;       for (int it = 0; it < N / 4 / NT; ++it) {
;         int idx = tid + it * NT;
;         int j = idx & (q - 1), blk = idx >> lq;
;         int p0 = blk * 4 * q + j;
;         float f = (float)j * inv4q;
;         float2 t1 = make_float2(cos_t(f), sin_t(f));
;         float2 t2 = cmul(t1, t1);
;         float2 x0 = s[phys(p0)], x1 = s[phys(p0 + q)], x2 = s[phys(p0 + 2 * q)], x3 = s[phys(p0 + 3 * q)];
;         float2 b = cmul(x1, t2);
;         float2 a0 = make_float2(x0.x + b.x, x0.y + b.y), a1 = make_float2(x0.x - b.x, x0.y - b.y);
;         b = cmul(x3, t2);
;         float2 a2 = make_float2(x2.x + b.x, x2.y + b.y), a3 = make_float2(x2.x - b.x, x2.y - b.y);
;         b = cmul(a2, t1);
;         s[phys(p0)] = make_float2(a0.x + b.x, a0.y + b.y);
;         s[phys(p0 + 2 * q)] = make_float2(a0.x - b.x, a0.y - b.y);
;         float2 c3 = cmul(a3, t1);
;         b = make_float2(-c3.y, c3.x);
;         s[phys(p0 + q)] = make_float2(a1.x + b.x, a1.y + b.y);
;         s[phys(p0 + 3 * q)] = make_float2(a1.x - b.x, a1.y - b.y);
;       }
;     }
	v_pk_mul_f32 v[6:7], v[16:17], v[6:7]
	v_mov_b32_e32 v21, v13
	v_pk_fma_f32 v[18:19], v[16:17], v[8:9], v[6:7] op_sel:[0,0,1] op_sel_hi:[1,1,0]
	v_pk_fma_f32 v[6:7], v[16:17], v[8:9], v[6:7] op_sel:[0,0,1] op_sel_hi:[1,0,0] neg_lo:[1,0,0] neg_hi:[1,0,0]
	v_pk_add_f32 v[12:13], v[10:11], v[20:21] neg_lo:[0,1] neg_hi:[0,1]
	v_mov_b32_e32 v19, v7
	v_pk_add_f32 v[8:9], v[10:11], v[20:21]
	v_pk_add_f32 v[10:11], v[14:15], v[18:19] op_sel:[1,0] op_sel_hi:[0,1]
	v_pk_add_f32 v[6:7], v[14:15], v[18:19] op_sel:[1,0] op_sel_hi:[0,1] neg_lo:[0,1] neg_hi:[0,1]
	v_mov_b32_e32 v14, v5
	v_mov_b32_e32 v16, v5
	v_pk_mul_f32 v[18:19], v[4:5], v[10:11] op_sel_hi:[0,1]
	v_pk_fma_f32 v[14:15], v[14:15], v[10:11], v[18:19] op_sel:[0,0,1] op_sel_hi:[1,1,0] neg_lo:[1,0,0] neg_hi:[1,0,0]
	v_pk_fma_f32 v[10:11], v[16:17], v[10:11], v[18:19] op_sel:[0,0,1] op_sel_hi:[0,1,0]
	v_mov_b32_e32 v15, v11
	v_pk_add_f32 v[10:11], v[8:9], v[14:15]
	v_pk_add_f32 v[8:9], v[8:9], v[14:15] neg_lo:[0,1] neg_hi:[0,1]
	ds_write_b64 v22, v[10:11]
	ds_write_b64 v24, v[8:9]
	v_pk_mul_f32 v[8:9], v[16:17], v[6:7] op_sel_hi:[0,1]
	v_pk_fma_f32 v[10:11], v[4:5], v[6:7], v[8:9] op_sel:[0,0,1] op_sel_hi:[1,1,0]
	v_pk_fma_f32 v[4:5], v[4:5], v[6:7], v[8:9] op_sel:[0,0,1] op_sel_hi:[0,1,0] neg_lo:[0,0,1] neg_hi:[0,0,1]
	v_mov_b32_e32 v11, v5
	v_pk_add_f32 v[4:5], v[12:13], v[10:11] neg_lo:[0,1] neg_hi:[0,1]
	v_pk_add_f32 v[6:7], v[12:13], v[10:11]
	v_mov_b32_e32 v8, v4
	v_mov_b32_e32 v9, v7
	v_add_u32_e32 v4, 0x400, v3
	ds_write_b64 v23, v[8:9]
	v_and_b32_e32 v9, s10, v4
	v_ashrrev_i32_e32 v4, s0, v4
	v_lshlrev_b32_e32 v10, 2, v4
	v_lshl_add_u32 v11, v10, s0, v9
	v_cvt_f32_u32_e32 v4, v9
	v_ashrrev_i32_e32 v12, 4, v11
	v_add_lshl_u32 v22, v12, v11, 3
	v_mul_f32_e32 v4, s5, v4
	v_mov_b32_e32 v7, v5
	v_fract_f32_e32 v5, v4
	v_cos_f32_e32 v4, v5
	v_sin_f32_e32 v5, v5
	ds_write_b64 v25, v[6:7]
	v_add_u32_e32 v23, s32, v22
	v_add_u32_e32 v24, s32, v23
	v_add_u32_e32 v25, s32, v24
	ds_read_b64 v[10:11], v22
	ds_read_b64 v[12:13], v23
	ds_read_b64 v[14:15], v24
	ds_read_b64 v[16:17], v25
	v_mul_f32_e32 v8, v4, v5
	v_pk_mul_f32 v[6:7], v[4:5], v[4:5]
	v_add_f32_e32 v8, v8, v8
	s_waitcnt lgkmcnt(2)
	v_pk_mul_f32 v[18:19], v[12:13], v[8:9] op_sel_hi:[1,0]
	v_pk_add_f32 v[6:7], v[6:7], v[6:7] op_sel:[0,1] op_sel_hi:[0,1] neg_lo:[0,1] neg_hi:[0,1]
	v_pk_fma_f32 v[20:21], v[12:13], v[6:7], v[18:19] op_sel:[0,0,1] op_sel_hi:[1,1,0] neg_lo:[0,0,1] neg_hi:[0,0,1]
	v_pk_fma_f32 v[12:13], v[12:13], v[6:7], v[18:19] op_sel:[0,0,1] op_sel_hi:[1,1,0]
	s_waitcnt lgkmcnt(0)
	v_pk_mul_f32 v[6:7], v[16:17], v[6:7]
	v_mov_b32_e32 v21, v13
	v_pk_fma_f32 v[18:19], v[16:17], v[8:9], v[6:7] op_sel:[0,0,1] op_sel_hi:[1,1,0]
	v_pk_fma_f32 v[6:7], v[16:17], v[8:9], v[6:7] op_sel:[0,0,1] op_sel_hi:[1,0,0] neg_lo:[1,0,0] neg_hi:[1,0,0]
	v_pk_add_f32 v[12:13], v[10:11], v[20:21] neg_lo:[0,1] neg_hi:[0,1]
	v_mov_b32_e32 v19, v7
	v_pk_add_f32 v[8:9], v[10:11], v[20:21]
	v_pk_add_f32 v[10:11], v[14:15], v[18:19] op_sel:[1,0] op_sel_hi:[0,1]
	v_pk_add_f32 v[6:7], v[14:15], v[18:19] op_sel:[1,0] op_sel_hi:[0,1] neg_lo:[0,1] neg_hi:[0,1]
	v_mov_b32_e32 v14, v5
	v_mov_b32_e32 v16, v5
	v_pk_mul_f32 v[18:19], v[4:5], v[10:11] op_sel_hi:[0,1]
	v_pk_fma_f32 v[14:15], v[14:15], v[10:11], v[18:19] op_sel:[0,0,1] op_sel_hi:[1,1,0] neg_lo:[1,0,0] neg_hi:[1,0,0]
	v_pk_fma_f32 v[10:11], v[16:17], v[10:11], v[18:19] op_sel:[0,0,1] op_sel_hi:[0,1,0]
	v_mov_b32_e32 v15, v11
	v_pk_add_f32 v[10:11], v[8:9], v[14:15]
	v_pk_add_f32 v[8:9], v[8:9], v[14:15] neg_lo:[0,1] neg_hi:[0,1]
	ds_write_b64 v22, v[10:11]
	ds_write_b64 v24, v[8:9]
	v_pk_mul_f32 v[8:9], v[16:17], v[6:7] op_sel_hi:[0,1]
	v_pk_fma_f32 v[10:11], v[4:5], v[6:7], v[8:9] op_sel:[0,0,1] op_sel_hi:[1,1,0]
	v_pk_fma_f32 v[4:5], v[4:5], v[6:7], v[8:9] op_sel:[0,0,1] op_sel_hi:[0,1,0] neg_lo:[0,0,1] neg_hi:[0,0,1]
	v_mov_b32_e32 v11, v5
	v_pk_add_f32 v[4:5], v[12:13], v[10:11] neg_lo:[0,1] neg_hi:[0,1]
	v_pk_add_f32 v[6:7], v[12:13], v[10:11]
	v_mov_b32_e32 v8, v4
	v_mov_b32_e32 v9, v7
	v_add_u32_e32 v3, 0x600, v3
	ds_write_b64 v23, v[8:9]
	v_and_b32_e32 v9, s10, v3
	v_ashrrev_i32_e32 v3, s0, v3
	v_lshlrev_b32_e32 v3, 2, v3
	v_lshl_add_u32 v10, v3, s0, v9
	v_cvt_f32_u32_e32 v4, v9
	v_ashrrev_i32_e32 v11, 4, v10
	v_add_lshl_u32 v22, v11, v10, 3
	v_mul_f32_e32 v4, s5, v4
	v_mov_b32_e32 v7, v5
	v_fract_f32_e32 v5, v4
	v_cos_f32_e32 v4, v5
	v_sin_f32_e32 v5, v5
	ds_write_b64 v25, v[6:7]
	v_add_u32_e32 v23, s32, v22
	v_add_u32_e32 v24, s32, v23
	v_add_u32_e32 v3, s32, v24
	ds_read_b64 v[10:11], v22
	ds_read_b64 v[12:13], v23
	ds_read_b64 v[14:15], v24
	ds_read_b64 v[16:17], v3
	v_mul_f32_e32 v8, v4, v5
	v_pk_mul_f32 v[6:7], v[4:5], v[4:5]
	v_add_f32_e32 v8, v8, v8
	s_waitcnt lgkmcnt(2)
	v_pk_mul_f32 v[18:19], v[12:13], v[8:9] op_sel_hi:[1,0]
	v_pk_add_f32 v[6:7], v[6:7], v[6:7] op_sel:[0,1] op_sel_hi:[0,1] neg_lo:[0,1] neg_hi:[0,1]
	v_pk_fma_f32 v[20:21], v[12:13], v[6:7], v[18:19] op_sel:[0,0,1] op_sel_hi:[1,1,0] neg_lo:[0,0,1] neg_hi:[0,0,1]
	v_pk_fma_f32 v[12:13], v[12:13], v[6:7], v[18:19] op_sel:[0,0,1] op_sel_hi:[1,1,0]
	s_waitcnt lgkmcnt(0)
	v_pk_mul_f32 v[6:7], v[16:17], v[6:7]
	v_mov_b32_e32 v21, v13
	v_pk_fma_f32 v[18:19], v[16:17], v[8:9], v[6:7] op_sel:[0,0,1] op_sel_hi:[1,1,0]
	v_pk_fma_f32 v[6:7], v[16:17], v[8:9], v[6:7] op_sel:[0,0,1] op_sel_hi:[1,0,0] neg_lo:[1,0,0] neg_hi:[1,0,0]
	v_pk_add_f32 v[12:13], v[10:11], v[20:21] neg_lo:[0,1] neg_hi:[0,1]
	v_mov_b32_e32 v19, v7
	v_pk_add_f32 v[8:9], v[10:11], v[20:21]
	v_pk_add_f32 v[10:11], v[14:15], v[18:19] op_sel:[1,0] op_sel_hi:[0,1]
	v_pk_add_f32 v[6:7], v[14:15], v[18:19] op_sel:[1,0] op_sel_hi:[0,1] neg_lo:[0,1] neg_hi:[0,1]
	v_mov_b32_e32 v14, v5
	v_mov_b32_e32 v16, v5
	v_pk_mul_f32 v[18:19], v[4:5], v[10:11] op_sel_hi:[0,1]
	v_pk_fma_f32 v[14:15], v[14:15], v[10:11], v[18:19] op_sel:[0,0,1] op_sel_hi:[1,1,0] neg_lo:[1,0,0] neg_hi:[1,0,0]
	v_pk_fma_f32 v[10:11], v[16:17], v[10:11], v[18:19] op_sel:[0,0,1] op_sel_hi:[0,1,0]
	v_mov_b32_e32 v15, v11
	v_pk_add_f32 v[10:11], v[8:9], v[14:15]
	v_pk_add_f32 v[8:9], v[8:9], v[14:15] neg_lo:[0,1] neg_hi:[0,1]
	ds_write_b64 v22, v[10:11]
	ds_write_b64 v24, v[8:9]
	v_pk_mul_f32 v[8:9], v[16:17], v[6:7] op_sel_hi:[0,1]
	v_pk_fma_f32 v[10:11], v[4:5], v[6:7], v[8:9] op_sel:[0,0,1] op_sel_hi:[1,1,0]
	v_pk_fma_f32 v[4:5], v[4:5], v[6:7], v[8:9] op_sel:[0,0,1] op_sel_hi:[0,1,0] neg_lo:[0,0,1] neg_hi:[0,0,1]
	v_mov_b32_e32 v11, v5
	v_pk_add_f32 v[4:5], v[12:13], v[10:11] neg_lo:[0,1] neg_hi:[0,1]
	v_pk_add_f32 v[6:7], v[12:13], v[10:11]
	s_addk_i32 s11, 0x800
	v_mov_b32_e32 v8, v4
	v_mov_b32_e32 v9, v7
	v_mov_b32_e32 v7, v5
	s_cmpk_lg_i32 s11, 0x1000
	ds_write_b64 v23, v[8:9]
	ds_write_b64 v3, v[6:7]
	s_cbranch_scc1 .Lfft_fast_3
; DI unsigned pack2(float a, float b) { fl2_t f = {a, b}; bf2_t r = __builtin_convertvector(f, bf2_t); return __builtin_bit_cast(unsigned, r); }
; DI void hyena_lat_item(const P& p, int l, int c, int bp, unsigned char* lds) {
;     ...
;     const float bias = p.in[I_HBIAS][l * 512 + ord * 256 + c];
;     if (ord == 0) {
;       float2 y1v[16];
; #pragma unroll
;       for (int i = 0; i < 16; ++i) {
;         int n = (i >> 3) * 4096 + tid * 8 + (i & 7);
;         float2 cv = s[phys(n)], v = scr[n], x1 = scr[8192 + n];
;         y1v[i] = make_float2(x1.x * (cv.x * invN + v.x * bias), x1.y * (cv.y * invN + v.y * bias));
;         scr[24576 + n] = y1v[i];
;       }
;       __syncthreads();
; #pragma unroll
;       for (int i = 0; i < 16; ++i) { int n = (i >> 3) * 4096 + tid * 8 + (i & 7); s[phys(n)] = y1v[i]; s[phys(n + L)] = make_float2(0.f, 0.f); }
;     } else {
;       u16* HYT = (u16*)(p.ws + O_HYT);
; #pragma unroll
;       for (int ch = 0; ch < 2; ++ch) {
;         float r0[8], r1[8];
; #pragma unroll
;         for (int e = 0; e < 8; ++e) {
;           int n = ch * 4096 + tid * 8 + e;
;           float2 cv = s[phys(n)], y1 = scr[24576 + n], x2 = scr[16384 + n];
;           r0[e] = x2.x * (cv.x * invN + y1.x * bias);
;           r1[e] = x2.y * (cv.y * invN + y1.y * bias);
;         }
;         *(uint4*)(HYT + ((size_t)(2 * bp) * 256 + c) * L + ch * 4096 + tid * 8) = make_uint4(pack2(r0[0], r0[1]), pack2(r0[2], r0[3]), pack2(r0[4], r0[5]), pack2(r0[6], r0[7]));
;         *(uint4*)(HYT + ((size_t)(2 * bp + 1) * 256 + c) * L + ch * 4096 + tid * 8) = make_uint4(pack2(r1[0], r1[1]), pack2(r1[2], r1[3]), pack2(r1[4], r1[5]), pack2(r1[6], r1[7]));
;       }
.Lfft_done_3:
	s_add_i32 s5, s0, 2
	s_cmp_lt_u32 s0, 11
	s_mov_b32 s1, s4
	s_mov_b32 s0, s5
	s_cbranch_scc1 .LBB0_500
	s_lshl_b32 s4, s34, 9
	s_or_b32 s0, s4, 0x100
	s_add_u32 s0, s0, s6
	s_addc_u32 s1, 0, s7
	s_lshl_b64 s[0:1], s[0:1], 14
	s_add_u32 s4, s4, s6
	v_readlane_b32 s16, v252, 46
	s_addc_u32 s5, 0, s7
	s_add_i32 s54, s6, s71
	v_readlane_b32 s18, v252, 48
	v_readlane_b32 s19, v252, 49
	v_readlane_b32 s22, v252, 52
	v_readlane_b32 s23, v252, 53
	s_lshl_b64 s[4:5], s[4:5], 14
	s_lshl_b64 s[6:7], s[54:55], 2
	s_mov_b64 s[18:19], s[22:23]
	s_add_u32 s6, s18, s6
	s_addc_u32 s7, s19, s7
	s_waitcnt lgkmcnt(0)
	s_barrier
	global_load_dword v18, v179, s[6:7]
	v_readlane_b32 s6, v253, 18
	s_add_u32 s4, s6, s4
	v_readlane_b32 s7, v253, 19
	s_addc_u32 s5, s7, s5
	s_add_u32 s0, s6, s0
	v_lshlrev_b64 v[2:3], 1, v[50:51]
	s_addc_u32 s1, s7, s1
	v_lshl_add_u64 v[16:17], s[4:5], 0, v[2:3]
	v_lshl_add_u64 v[14:15], s[0:1], 0, v[2:3]
	ds_read2_b64 v[24:27], v63 offset1:1
	global_load_dwordx4 v[2:5], v[60:61], off offset:48
	global_load_dwordx4 v[10:13], v[60:61], off offset:32
	global_load_dwordx4 v[34:37], v[60:61], off offset:16
	global_load_dwordx4 v[40:43], v[60:61], off
	v_add_co_u32_e32 v6, vcc, s51, v58
	s_mov_b64 s[0:1], 0x20000
	s_nop 0
	v_addc_co_u32_e32 v7, vcc, 0, v59, vcc
	v_lshl_add_u64 v[20:21], v[58:59], 0, s[0:1]
	global_load_dwordx4 v[50:53], v[6:7], off
	s_nop 0
	global_load_dwordx4 v[6:9], v[20:21], off offset:48
	global_load_dwordx4 v[58:61], v[20:21], off offset:32
	global_load_dwordx4 v[64:67], v[20:21], off offset:16
	s_waitcnt lgkmcnt(0)
	v_mov_b32_e32 v20, v24
	v_mov_b32_e32 v21, v26
	s_mov_b32 s4, 0x38800000
	v_mov_b32_e32 v26, v25
	v_readlane_b32 s20, v252, 50
	v_readlane_b32 s21, v252, 51
	v_readlane_b32 s24, v252, 54
	v_readlane_b32 s25, v252, 55
	v_readlane_b32 s26, v252, 56
	v_readlane_b32 s27, v252, 57
	v_readlane_b32 s28, v252, 58
	v_readlane_b32 s29, v252, 59
	v_readlane_b32 s30, v252, 60
	v_readlane_b32 s31, v252, 61
	s_mov_b64 s[20:21], s[24:25]
	v_readlane_b32 s17, v252, 47
	s_mov_b64 s[22:23], s[26:27]
	s_mov_b64 s[24:25], s[28:29]
	s_mov_b64 s[26:27], s[30:31]
	s_waitcnt vmcnt(4)
	v_mov_b32_e32 v22, v40
	v_mov_b32_e32 v23, v42
	v_pk_mul_f32 v[22:23], v[18:19], v[22:23] op_sel_hi:[0,1]
	v_pk_fma_f32 v[20:21], v[20:21], s[4:5], v[22:23] op_sel_hi:[1,0,1]
	s_waitcnt vmcnt(3)
	v_mov_b32_e32 v22, v50
	v_mov_b32_e32 v23, v52
	v_mov_b32_e32 v42, v41
	v_pk_mul_f32 v[22:23], v[22:23], v[20:21]
	v_pk_mul_f32 v[20:21], v[18:19], v[42:43] op_sel_hi:[0,1]
	ds_read2_b64 v[40:43], v63 offset0:2 offset1:3
	v_pk_fma_f32 v[20:21], v[26:27], s[4:5], v[20:21] op_sel_hi:[1,0,1]
	v_mov_b32_e32 v26, v34
	v_mov_b32_e32 v27, v36
	v_pk_mul_f32 v[26:27], v[18:19], v[26:27] op_sel_hi:[0,1]
	s_waitcnt lgkmcnt(0)
	v_mov_b32_e32 v24, v40
	v_mov_b32_e32 v25, v42
	v_pk_fma_f32 v[24:25], v[24:25], s[4:5], v[26:27] op_sel_hi:[1,0,1]
	s_waitcnt vmcnt(0)
	v_mov_b32_e32 v26, v64
	v_mov_b32_e32 v27, v66
	v_mov_b32_e32 v36, v35
	v_pk_mul_f32 v[26:27], v[26:27], v[24:25]
	v_pk_mul_f32 v[24:25], v[18:19], v[36:37] op_sel_hi:[0,1]
	ds_read2_b64 v[34:37], v63 offset0:4 offset1:5
	v_mov_b32_e32 v42, v41
	v_mov_b32_e32 v41, v12
	v_mov_b32_e32 v12, v11
	v_mov_b32_e32 v40, v10
	s_waitcnt lgkmcnt(0)
	v_mov_b32_e32 v29, v36
	v_mov_b32_e32 v36, v35
	v_pk_mul_f32 v[10:11], v[18:19], v[12:13] op_sel_hi:[0,1]
	v_mov_b32_e32 v28, v34
	v_pk_fma_f32 v[10:11], v[36:37], s[4:5], v[10:11] op_sel_hi:[1,0,1]
	ds_read2_b64 v[34:37], v63 offset0:6 offset1:7
	v_pk_mul_f32 v[40:41], v[18:19], v[40:41] op_sel_hi:[0,1]
	v_pk_fma_f32 v[28:29], v[28:29], s[4:5], v[40:41] op_sel_hi:[1,0,1]
	v_mov_b32_e32 v40, v58
	v_mov_b32_e32 v41, v60
	v_pk_mul_f32 v[28:29], v[40:41], v[28:29]
	v_mov_b32_e32 v40, v2
	v_mov_b32_e32 v41, v4
	s_waitcnt lgkmcnt(0)
; DI unsigned pack2(float a, float b) { fl2_t f = {a, b}; bf2_t r = __builtin_convertvector(f, bf2_t); return __builtin_bit_cast(unsigned, r); }
; DI void hyena_lat_item(const P& p, int l, int c, int bp, unsigned char* lds) {
;     ...
;       u16* HYT = (u16*)(p.ws + O_HYT);
; #pragma unroll
;       for (int ch = 0; ch < 2; ++ch) {
;         float r0[8], r1[8];
; #pragma unroll
;         for (int e = 0; e < 8; ++e) {
;           int n = ch * 4096 + tid * 8 + e;
;           float2 cv = s[phys(n)], y1 = scr[24576 + n], x2 = scr[16384 + n];
;           r0[e] = x2.x * (cv.x * invN + y1.x * bias);
;           r1[e] = x2.y * (cv.y * invN + y1.y * bias);
;         }
;         *(uint4*)(HYT + ((size_t)(2 * bp) * 256 + c) * L + ch * 4096 + tid * 8) = make_uint4(pack2(r0[0], r0[1]), pack2(r0[2], r0[3]), pack2(r0[4], r0[5]), pack2(r0[6], r0[7]));
;         *(uint4*)(HYT + ((size_t)(2 * bp + 1) * 256 + c) * L + ch * 4096 + tid * 8) = make_uint4(pack2(r1[0], r1[1]), pack2(r1[2], r1[3]), pack2(r1[4], r1[5]), pack2(r1[6], r1[7]));
;       }
;     }
;   }
;   __syncthreads();
	v_mov_b32_e32 v12, v34
	v_mov_b32_e32 v13, v36
	v_pk_mul_f32 v[40:41], v[18:19], v[40:41] op_sel_hi:[0,1]
	v_mov_b32_e32 v4, v3
	v_pk_fma_f32 v[12:13], v[12:13], s[4:5], v[40:41] op_sel_hi:[1,0,1]
	v_mov_b32_e32 v40, v6
	v_mov_b32_e32 v41, v8
	v_mov_b32_e32 v36, v35
	v_pk_mul_f32 v[2:3], v[18:19], v[4:5] op_sel_hi:[0,1]
	v_mov_b32_e32 v52, v51
	v_pk_fma_f32 v[24:25], v[42:43], s[4:5], v[24:25] op_sel_hi:[1,0,1]
	v_mov_b32_e32 v66, v65
	v_mov_b32_e32 v60, v59
	v_pk_mul_f32 v[12:13], v[40:41], v[12:13]
	v_pk_fma_f32 v[2:3], v[36:37], s[4:5], v[2:3] op_sel_hi:[1,0,1]
	v_mov_b32_e32 v8, v7
	v_pk_mul_f32 v[20:21], v[52:53], v[20:21]
	v_pk_mul_f32 v[24:25], v[66:67], v[24:25]
	v_pk_mul_f32 v[10:11], v[60:61], v[10:11]
	v_pk_mul_f32 v[6:7], v[8:9], v[2:3]
	v_cvt_pk_bf16_f32 v2, v22, v23
	v_cvt_pk_bf16_f32 v3, v26, v27
	v_cvt_pk_bf16_f32 v4, v28, v29
	v_cvt_pk_bf16_f32 v5, v12, v13
	global_store_dwordx4 v[16:17], v[2:5], off
	ds_read2_b64 v[34:37], v1 offset1:1
	v_lshl_add_u64 v[26:27], v[54:55], 0, s[0:1]
	v_cvt_pk_bf16_f32 v2, v20, v21
	v_cvt_pk_bf16_f32 v3, v24, v25
	v_cvt_pk_bf16_f32 v4, v10, v11
	v_cvt_pk_bf16_f32 v5, v6, v7
	global_store_dwordx4 v[14:15], v[2:5], off
	global_load_dwordx2 v[24:25], v[48:49], off
	s_waitcnt vmcnt(0)
	v_mov_b32_e32 v52, v24
	v_add_co_u32_e32 v2, vcc, s51, v46
	s_nop 1
	v_addc_co_u32_e32 v3, vcc, 0, v47, vcc
	global_load_dwordx2 v[28:29], v[2:3], off
	global_load_dwordx2 v[20:21], v[56:57], off offset:48
	s_nop 0
	global_load_dwordx4 v[2:5], v[56:57], off offset:32
	global_load_dwordx4 v[10:13], v[56:57], off offset:16
	global_load_dwordx4 v[40:43], v[56:57], off
	v_add_co_u32_e32 v6, vcc, s51, v54
	s_waitcnt vmcnt(1)
	v_mov_b32_e32 v39, v10
	v_addc_co_u32_e32 v7, vcc, 0, v55, vcc
	global_load_dwordx4 v[44:47], v[6:7], off
	global_load_dwordx2 v[22:23], v[26:27], off offset:48
	s_nop 0
	global_load_dwordx4 v[6:9], v[26:27], off offset:32
	global_load_dwordx4 v[48:51], v[26:27], off offset:16
	s_waitcnt vmcnt(4)
	v_mov_b32_e32 v53, v40
	v_mov_b32_e32 v40, v25
	s_waitcnt lgkmcnt(0)
	v_mov_b32_e32 v27, v36
	v_mov_b32_e32 v36, v35
	v_pk_mul_f32 v[24:25], v[18:19], v[40:41] op_sel_hi:[0,1]
	v_mov_b32_e32 v26, v34
	v_pk_fma_f32 v[24:25], v[36:37], s[4:5], v[24:25] op_sel_hi:[1,0,1]
	ds_read2_b64 v[34:37], v38 offset1:1
	v_pk_mul_f32 v[52:53], v[18:19], v[52:53] op_sel_hi:[0,1]
	v_mov_b32_e32 v10, v43
	v_pk_fma_f32 v[26:27], v[26:27], s[4:5], v[52:53] op_sel_hi:[1,0,1]
	v_pk_mul_f32 v[10:11], v[18:19], v[10:11] op_sel_hi:[0,1]
	v_mov_b32_e32 v52, v28
	s_waitcnt lgkmcnt(0)
	v_mov_b32_e32 v28, v34
	v_mov_b32_e32 v38, v42
	v_pk_mul_f32 v[38:39], v[18:19], v[38:39] op_sel_hi:[0,1]
	s_waitcnt vmcnt(3)
	v_mov_b32_e32 v53, v44
	v_mov_b32_e32 v44, v29
	v_mov_b32_e32 v29, v36
	v_mov_b32_e32 v36, v35
	v_pk_fma_f32 v[10:11], v[36:37], s[4:5], v[10:11] op_sel_hi:[1,0,1]
	ds_read2_b64 v[34:37], v30 offset1:1
	v_pk_fma_f32 v[28:29], v[28:29], s[4:5], v[38:39] op_sel_hi:[1,0,1]
	v_mov_b32_e32 v38, v46
	s_waitcnt vmcnt(0)
	v_mov_b32_e32 v39, v48
	v_pk_mul_f32 v[28:29], v[38:39], v[28:29]
	s_waitcnt lgkmcnt(0)
	v_mov_b32_e32 v30, v34
	v_mov_b32_e32 v31, v36
	v_mov_b32_e32 v36, v35
	ds_read2_b64 v[32:35], v32 offset1:1
	v_mov_b32_e32 v38, v12
	v_mov_b32_e32 v39, v2
	v_mov_b32_e32 v2, v13
	v_pk_mul_f32 v[38:39], v[18:19], v[38:39] op_sel_hi:[0,1]
	v_pk_mul_f32 v[2:3], v[18:19], v[2:3] op_sel_hi:[0,1]
	v_pk_fma_f32 v[30:31], v[30:31], s[4:5], v[38:39] op_sel_hi:[1,0,1]
	v_mov_b32_e32 v39, v6
	v_pk_fma_f32 v[2:3], v[36:37], s[4:5], v[2:3] op_sel_hi:[1,0,1]
	v_mov_b32_e32 v6, v51
	v_mov_b32_e32 v12, v4
	v_mov_b32_e32 v13, v20
	v_pk_mul_f32 v[2:3], v[6:7], v[2:3]
	s_waitcnt lgkmcnt(0)
	v_mov_b32_e32 v6, v32
	v_mov_b32_e32 v7, v34
	v_pk_mul_f32 v[12:13], v[18:19], v[12:13] op_sel_hi:[0,1]
	v_pk_fma_f32 v[6:7], v[6:7], s[4:5], v[12:13] op_sel_hi:[1,0,1]
	v_mov_b32_e32 v12, v8
	v_mov_b32_e32 v13, v22
	v_mov_b32_e32 v20, v5
	v_mov_b32_e32 v38, v50
	v_pk_mul_f32 v[12:13], v[12:13], v[6:7]
	v_mov_b32_e32 v34, v33
	v_pk_mul_f32 v[4:5], v[18:19], v[20:21] op_sel_hi:[0,1]
	v_pk_mul_f32 v[26:27], v[52:53], v[26:27]
	v_pk_mul_f32 v[30:31], v[38:39], v[30:31]
	v_pk_fma_f32 v[4:5], v[34:35], s[4:5], v[4:5] op_sel_hi:[1,0,1]
	v_mov_b32_e32 v22, v9
	v_cvt_pk_bf16_f32 v7, v12, v13
	v_add_co_u32_e32 v12, vcc, s91, v16
	v_mov_b32_e32 v48, v47
	v_pk_mul_f32 v[8:9], v[22:23], v[4:5]
	v_cvt_pk_bf16_f32 v4, v26, v27
	v_cvt_pk_bf16_f32 v5, v28, v29
	v_cvt_pk_bf16_f32 v6, v30, v31
	v_addc_co_u32_e32 v13, vcc, 0, v17, vcc
	v_pk_mul_f32 v[24:25], v[44:45], v[24:25]
	v_pk_mul_f32 v[10:11], v[48:49], v[10:11]
	global_store_dwordx4 v[12:13], v[4:7], off
	s_nop 1
	v_cvt_pk_bf16_f32 v6, v2, v3
	v_add_co_u32_e32 v2, vcc, 0x2000, v14
	v_cvt_pk_bf16_f32 v4, v24, v25
	v_cvt_pk_bf16_f32 v5, v10, v11
	v_cvt_pk_bf16_f32 v7, v8, v9
	v_addc_co_u32_e32 v3, vcc, 0, v15, vcc
	global_store_dwordx4 v[2:3], v[4:7], off
	s_barrier
